# P3 EpiZ: per-row rms scale of blocks 1..7 cached in VGPRs across the two tiles of a workgroup (same row panel)
# speedup vs baseline: 1.0093x; 1.0093x over previous
;     __host__ __device__ bool next(int i, Unit& u) const {
;         const long L = (long)i * G + c; if (L >= nwg) return false;
;         int wgid = (int)L; { const int q = nwg / NXCD, r = nwg % NXCD, xcd = wgid % NXCD, off = wgid / NXCD; wgid = (xcd < r ? xcd * (q + 1) : r * (q + 1) + (xcd - r) * q) + off; }
;         const int nig = WGM * nN, gid = wgid / nig, fm = gid * WGM, gsz = (nM - fm) < WGM ? (nM - fm) : WGM;
;         u.pm = fm + ((wgid % nig) % gsz); u.pn = (wgid % nig) / gsz; return true;
; __global__ void __launch_bounds__(NTHR, 2) fwd_kernel(Args args) {
;     ...
;     if (IN(3)) {
;         pg8::Gemm g{hhi1, (const bf16_t*)(ws + WS_WIN), T_, FF_, D_}; pg8::StaticOrder S; S.init(T_, FF_, C.G, C.bid);
;         EpiZ E{(bf16_t*)(ws + WS_ZR), (bf16_t*)(ws + WS_ZG), ssqB, (float*)(ws + WS_LNST)};
;         pg8::gemm_phase<EpiZ, pg8::StaticOrder, true, true>(C.lds, g, S, E);
.LBB0_566:
	s_mov_b32 s100, -1
	s_cmp_lt_i32 s76, 4
	s_cselect_b64 s[0:1], -1, 0
	s_and_b64 s[64:65], s[0:1], s[6:7]
	s_andn2_b64 vcc, exec, s[64:65]
	s_cbranch_vccnz .LBB0_657
	s_cmpk_lt_i32 s94, 0x2c0
	s_cselect_b64 s[6:7], -1, 0
	s_cmpk_gt_i32 s94, 0x2bf
	v_readfirstlane_b32 s0, v0
	s_cbranch_scc1 .LBB0_569
	s_ashr_i32 s1, s94, 31
	s_lshr_b32 s1, s1, 29
	s_add_i32 s1, s94, s1
	s_ashr_i32 s2, s1, 3
	s_and_b32 s1, s1, -8
	s_sub_i32 s1, s94, s1
	s_cmp_lt_i32 s1, 0
	s_movk_i32 s3, 0x59
	s_cselect_b32 s3, s3, 0x58
	s_mul_i32 s1, s1, s3
	s_add_i32 s1, s1, s2
	s_mul_hi_i32 s2, s1, 0x2e8ba2e9
	s_lshr_b32 s3, s2, 31
	s_ashr_i32 s2, s2, 4
	s_add_i32 s2, s2, s3
	s_lshl_b32 s3, s2, 3
	s_mulk_i32 s2, 0x58
	s_sub_i32 s1, s1, s2
	s_bfe_i32 s2, s1, 0x80000
	s_bfe_u32 s2, s2, 0x3000c
	s_add_i32 s2, s1, s2
	s_bfe_i32 s4, s2, 0x80000
	s_and_b32 s2, s2, 0xf8
	s_sub_i32 s1, s1, s2
	s_sext_i32_i16 s4, s4
	s_sext_i32_i8 s1, s1
	s_add_i32 s10, s3, s1
	s_ashr_i32 s16, s4, 3

; __device__ __forceinline__ float row_rstd_q(const float* ssq, int row, int fq) {
;     const f32x4 a = ((const f32x4*)(ssq + (size_t)row * 16))[fq];
;     float s = (a[0] + a[1]) + (a[2] + a[3]);
;     s += __shfl_xor(s, 16); s += __shfl_xor(s, 32);
;     return 1.0f / sqrtf(s * (1.0f / 1024.0f) + 1e-6f);
; }
;     __device__ __forceinline__ void operator()(const f32x4 (&acc)[2][2][4][2], const Unit& u, int wr, int wc, int fr, int fq) const {
;         const int row0 = u.pm * 256 + wr * 64 + fr; const bool isg = u.pn >= 7;
;         const int col0 = (isg ? (u.pn - 7) * 256 : u.pn * 256) + wc * 32 + 8 * fq;
;         bf16_t* basep = isg ? zg : zr; const int ld = isg ? 1024 : RC_;
; #pragma unroll
;         for (int ai = 0; ai < 2; ++ai)
; #pragma unroll
;             for (int m = 0; m < 4; ++m) {
;                 const int row = row0 + ai * 128 + m * 16; const float rs = row_rstd_q(ssq, row, fq); float s1 = 0.f, s2 = 0.f;
; #pragma unroll
;                 for (int bj = 0; bj < 2; ++bj) {
;                     f32x4 v0 = acc[ai][bj][m][0] * rs, v1 = acc[ai][bj][m][1] * rs;
.LBB0_581:
	s_cmp_eq_u32 s100, s10
	s_cselect_b32 s101, 1, 0
	s_mov_b32 s100, s10
	v_lshl_add_u32 v152, s10, 8, v1
	v_ashrrev_i32_e32 v153, 31, v152
	v_lshlrev_b64 v[154:155], 6, v[152:153]
	v_lshl_add_u64 v[156:157], v[140:141], 0, v[154:155]
	global_load_dwordx4 v[156:159], v[156:157], off
	v_and_b32_e32 v153, 64, v168
	v_xor_b32_e32 v139, 16, v168
	v_add_u32_e32 v162, 64, v153
	v_cmp_lt_i32_e32 vcc, v139, v162
	s_cmp_gt_i32 s16, 6
	s_cselect_b64 s[18:19], -1, 0
	v_cndmask_b32_e32 v139, v168, v139, vcc
	v_lshlrev_b32_e32 v153, 2, v139
	s_cmp_lt_i32 s16, 7
	s_waitcnt vmcnt(0)
	v_mov_b32_e32 v160, v157
	v_mov_b32_e32 v161, v158
	v_mov_b32_e32 v157, v159
	v_pk_add_f32 v[156:157], v[160:161], v[156:157]
	s_nop 0
	v_add_f32_e32 v139, v156, v157
	ds_bpermute_b32 v156, v153, v139
	v_xor_b32_e32 v157, 32, v168
	v_cmp_lt_i32_e32 vcc, v157, v162
	s_waitcnt lgkmcnt(0)
	v_add_f32_e32 v139, v139, v156
	v_cndmask_b32_e32 v157, v168, v157, vcc
	v_lshlrev_b32_e32 v171, 2, v157
	ds_bpermute_b32 v156, v171, v139
	s_waitcnt lgkmcnt(0)
	v_add_f32_e32 v139, v139, v156
	v_fmamk_f32 v139, v139, 0x3a800000, v169
	v_mul_f32_e32 v156, 0x4f800000, v139
	v_cmp_gt_f32_e32 vcc, s21, v139
	s_nop 1
	v_cndmask_b32_e32 v139, v139, v156, vcc
	v_sqrt_f32_e32 v156, v139
	s_nop 0
	v_add_u32_e32 v157, -1, v156
	v_add_u32_e32 v158, 1, v156
	v_fma_f32 v159, -v157, v156, v139
	v_fma_f32 v160, -v158, v156, v139
	v_cmp_ge_f32_e64 s[10:11], 0, v159
	s_nop 1
	v_cndmask_b32_e64 v156, v156, v157, s[10:11]
	v_cmp_lt_f32_e64 s[10:11], 0, v160
	s_nop 1
	v_cndmask_b32_e64 v156, v156, v158, s[10:11]
	v_mul_f32_e32 v157, 0x37800000, v156
	v_cndmask_b32_e32 v156, v156, v157, vcc
	v_cmp_class_f32_e32 vcc, v139, v170
	s_nop 1
	v_cndmask_b32_e32 v139, v156, v139, vcc
	v_div_scale_f32 v156, s[10:11], v139, v139, 1.0
	v_rcp_f32_e32 v157, v156
	v_div_scale_f32 v158, vcc, 1.0, v139, 1.0
	v_fma_f32 v159, -v156, v157, 1.0
	v_fmac_f32_e32 v157, v159, v157
	v_mul_f32_e32 v159, v158, v157
	v_fma_f32 v160, -v156, v159, v158
	v_fmac_f32_e32 v159, v160, v157
	v_fma_f32 v156, -v156, v159, v158
	v_div_fmas_f32 v156, v156, v157, v159
	v_div_fixup_f32 v156, v156, v139, 1.0
	v_pk_mul_f32 v[158:159], v[128:129], v[156:157] op_sel_hi:[1,0]
	v_pk_mul_f32 v[162:163], v[126:127], v[156:157] op_sel_hi:[1,0]
	v_pk_mul_f32 v[124:125], v[124:125], v[156:157] op_sel_hi:[1,0]
	v_pk_mul_f32 v[128:129], v[122:123], v[156:157] op_sel_hi:[1,0]
	s_cbranch_scc1 .LBB0_583
; __device__ __forceinline__ float frcp(float x) { return __builtin_amdgcn_rcpf(x); }
; __device__ __forceinline__ float gelu_erf(float v) {
;     const float av = fabsf(v), t = frcp(av * 0.2316418882f + 1.0f);
;     float qq = t * 0.5307027145f + (-0.7265760135f); qq = qq * t + 0.7107068705f; qq = qq * t + (-0.142248368f); qq = qq * t + 0.127414796f; qq = qq * t;
;     const float e = __builtin_amdgcn_exp2f((v * v) * (-0.72134752044f));
;     const float m = v * (qq * e);
;     return v < 0.f ? m : v - m;
; }
;     __device__ __forceinline__ void operator()(const f32x4 (&acc)[2][2][4][2], const Unit& u, int wr, int wc, int fr, int fq) const {
;     ...
;                     if (isg) {
; #pragma unroll
;                         for (int j = 0; j < 4; ++j) { v0[j] = gelu_erf(v0[j]); v1[j] = gelu_erf(v1[j]); }
;                         s1 += ((v0[0] + v0[1]) + (v0[2] + v0[3])) + ((v1[0] + v1[1]) + (v1[2] + v1[3]));
;                         s2 += ((v0[0] * v0[0] + v0[1] * v0[1]) + (v0[2] * v0[2] + v0[3] * v0[3])) + ((v1[0] * v1[0] + v1[1] * v1[1]) + (v1[2] * v1[2] + v1[3] * v1[3]));
;                     }
	v_fma_f32 v122, |v162|, s0, 1.0
	v_rcp_f32_e32 v123, v122
	v_fma_f32 v122, |v128|, s0, 1.0
	v_rcp_f32_e32 v122, v122
	v_mul_f32_e32 v126, v162, v162
	v_mul_f32_e32 v126, 0xbf38aa3b, v126
	v_mul_f32_e32 v139, v128, v128
	v_exp_f32_e32 v127, v126
	v_fmamk_f32 v126, v122, 0x3f07dc22, v150
	v_mul_f32_e32 v139, 0xbf38aa3b, v139
	v_fmaak_f32 v126, v122, v126, 0x3f35f0e3
	v_exp_f32_e32 v139, v139
	v_fmaak_f32 v126, v122, v126, 0xbe11a98e
	v_fmaak_f32 v126, v122, v126, 0x3e027906
	v_mul_f32_e32 v122, v122, v126
	v_mul_f32_e32 v160, v139, v122
	v_fma_f32 v122, |v163|, s0, 1.0
	v_rcp_f32_e32 v122, v122
	v_mul_f32_e32 v126, v163, v163
	v_mul_f32_e32 v126, 0xbf38aa3b, v126
	v_exp_f32_e32 v126, v126
	v_pk_fma_f32 v[172:173], v[122:123], s[48:49], v[150:151] op_sel_hi:[1,0,0]
	v_fma_f32 v139, |v129|, s0, 1.0
	v_pk_fma_f32 v[172:173], v[122:123], v[172:173], s[56:57] op_sel_hi:[1,1,0]
	v_rcp_f32_e32 v139, v139
	v_pk_fma_f32 v[172:173], v[122:123], v[172:173], s[60:61] op_sel_hi:[1,1,0]
	v_fma_f32 v157, |v158|, s0, 1.0
	v_pk_fma_f32 v[172:173], v[122:123], v[172:173], s[62:63] op_sel_hi:[1,1,0]
	v_rcp_f32_e32 v157, v157
	v_pk_mul_f32 v[122:123], v[122:123], v[172:173]
	v_fma_f32 v161, |v124|, s0, 1.0
	v_pk_mul_f32 v[122:123], v[126:127], v[122:123]
	v_mul_f32_e32 v127, v129, v129
	v_fmamk_f32 v126, v139, 0x3f07dc22, v150
	v_mul_f32_e32 v127, 0xbf38aa3b, v127
	v_fmaak_f32 v126, v139, v126, 0x3f35f0e3
	v_exp_f32_e32 v127, v127
	v_fmaak_f32 v126, v139, v126, 0xbe11a98e
	v_fmaak_f32 v126, v139, v126, 0x3e027906
	v_mul_f32_e32 v126, v139, v126
	v_mul_f32_e32 v139, v158, v158
	v_mul_f32_e32 v126, v127, v126
	v_fmamk_f32 v127, v157, 0x3f07dc22, v150
	v_mul_f32_e32 v139, 0xbf38aa3b, v139
	v_fmaak_f32 v127, v157, v127, 0x3f35f0e3
	v_exp_f32_e32 v139, v139
	v_fmaak_f32 v127, v157, v127, 0xbe11a98e
	v_rcp_f32_e32 v161, v161
	v_fmaak_f32 v127, v157, v127, 0x3e027906
	v_mul_f32_e32 v127, v157, v127
	v_mul_f32_e32 v172, v139, v127
	v_mul_f32_e32 v139, v124, v124
	v_fmamk_f32 v127, v161, 0x3f07dc22, v150
	v_mul_f32_e32 v139, 0xbf38aa3b, v139
	v_fmaak_f32 v127, v161, v127, 0x3f35f0e3
	v_exp_f32_e32 v139, v139
	v_fma_f32 v157, |v159|, s0, 1.0
	v_fmaak_f32 v127, v161, v127, 0xbe11a98e
	v_rcp_f32_e32 v157, v157
	v_fmaak_f32 v127, v161, v127, 0x3e027906
	v_mul_f32_e32 v127, v161, v127
	v_mul_f32_e32 v174, v139, v127
	v_mul_f32_e32 v139, v159, v159
	v_fmamk_f32 v127, v157, 0x3f07dc22, v150
	v_mul_f32_e32 v139, 0xbf38aa3b, v139
	v_fmaak_f32 v127, v157, v127, 0x3f35f0e3
	v_exp_f32_e32 v139, v139
	v_fma_f32 v161, |v125|, s0, 1.0
	v_fmaak_f32 v127, v157, v127, 0xbe11a98e
	v_rcp_f32_e32 v161, v161
	v_fmaak_f32 v127, v157, v127, 0x3e027906
	v_mul_f32_e32 v127, v157, v127
	v_mul_f32_e32 v176, v139, v127
	v_mul_f32_e32 v139, v125, v125
	v_fmamk_f32 v127, v161, 0x3f07dc22, v150
	v_mul_f32_e32 v139, 0xbf38aa3b, v139
	v_fmaak_f32 v127, v161, v127, 0x3f35f0e3
	v_exp_f32_e32 v139, v139
	v_fmaak_f32 v127, v161, v127, 0xbe11a98e
	v_fmaak_f32 v127, v161, v127, 0x3e027906
	v_mul_f32_e32 v127, v161, v127
	v_pk_mul_f32 v[180:181], v[162:163], v[122:123] op_sel:[1,0] op_sel_hi:[0,1]
	v_mov_b32_e32 v182, v159
	v_mov_b32_e32 v183, v163
	v_mov_b32_e32 v177, v122
	v_mov_b32_e32 v186, v158
	v_mov_b32_e32 v187, v163
	v_mov_b32_e32 v173, v122
	v_pk_fma_f32 v[122:123], v[162:163], v[122:123], v[162:163] op_sel:[1,0,1] op_sel_hi:[0,1,0] neg_lo:[1,0,0] neg_hi:[1,0,0]
	v_mov_b32_e32 v190, v128
	v_mov_b32_e32 v191, v158
	v_mov_b32_e32 v161, v172
	v_cmp_gt_f32_e64 s[10:11], 0, v162
	v_mul_f32_e32 v178, v139, v127
	v_pk_mul_f32 v[184:185], v[182:183], v[176:177]
	v_pk_mul_f32 v[188:189], v[186:187], v[172:173]
	v_pk_mul_f32 v[194:195], v[190:191], v[160:161]
	v_pk_mov_b32 v[196:197], v[128:129], v[158:159] op_sel:[1,0]
	v_mov_b32_e32 v127, v172
	v_mov_b32_e32 v200, v124
	v_mov_b32_e32 v201, v159
	v_mov_b32_e32 v175, v176
	v_pk_fma_f32 v[172:173], v[186:187], v[172:173], v[186:187] neg_lo:[1,0,0] neg_hi:[1,0,0]
	v_pk_fma_f32 v[160:161], v[190:191], v[160:161], v[190:191] neg_lo:[1,0,0] neg_hi:[1,0,0]
	v_cmp_gt_f32_e32 vcc, 0, v158
	v_mov_b32_e32 v179, v176
	v_pk_fma_f32 v[176:177], v[182:183], v[176:177], v[182:183] neg_lo:[1,0,0] neg_hi:[1,0,0]
	v_cndmask_b32_e64 v123, v123, v181, s[10:11]
	v_cmp_gt_f32_e64 s[10:11], 0, v163
	v_pk_mul_f32 v[198:199], v[196:197], v[126:127]
	v_pk_mul_f32 v[202:203], v[200:201], v[174:175]
	v_cndmask_b32_e64 v122, v122, v180, s[10:11]
	v_pk_fma_f32 v[126:127], v[196:197], v[126:127], v[196:197] neg_lo:[1,0,0] neg_hi:[1,0,0]
	v_cmp_gt_f32_e64 s[12:13], 0, v129
	v_cndmask_b32_e32 v129, v161, v195, vcc
	v_cndmask_b32_e64 v161, v173, v189, s[10:11]
	v_pk_fma_f32 v[162:163], v[200:201], v[174:175], v[200:201] neg_lo:[1,0,0] neg_hi:[1,0,0]
	v_cndmask_b32_e64 v175, v177, v185, s[10:11]
	v_cmp_gt_f32_e64 s[10:11], 0, v159
	v_mov_b32_e32 v158, v125
	v_cmp_gt_f32_e64 s[14:15], 0, v128
	v_cndmask_b32_e64 v174, v176, v184, s[10:11]
	v_cndmask_b32_e64 v176, v126, v198, s[12:13]
	v_mov_b32_e32 v126, v123
	v_pk_mul_f32 v[186:187], v[158:159], v[178:179]
	v_cndmask_b32_e64 v128, v160, v194, s[14:15]
	v_cndmask_b32_e32 v160, v172, v188, vcc
	v_pk_fma_f32 v[172:173], v[158:159], v[178:179], v[158:159] neg_lo:[1,0,0] neg_hi:[1,0,0]
	v_cndmask_b32_e32 v177, v127, v199, vcc
	v_cmp_gt_f32_e32 vcc, 0, v124
	v_pk_add_f32 v[126:127], v[126:127], v[122:123] op_sel_hi:[0,1]
	v_pk_mul_f32 v[158:159], v[122:123], v[122:123]
	v_cmp_gt_f32_e64 s[14:15], 0, v125
	v_cndmask_b32_e64 v125, v163, v203, s[10:11]
	v_cndmask_b32_e32 v124, v162, v202, vcc
	v_mov_b32_e32 v127, v159
	v_pk_add_f32 v[158:159], v[160:161], v[174:175]
	v_pk_mul_f32 v[162:163], v[160:161], v[174:175]
	v_cndmask_b32_e64 v173, v173, v187, s[10:11]
	v_mov_b32_e32 v159, v163
	v_cndmask_b32_e64 v172, v172, v186, s[14:15]
	v_pk_add_f32 v[126:127], v[126:127], v[158:159]
	v_pk_add_f32 v[158:159], v[128:129], v[176:177]
	v_pk_mul_f32 v[162:163], v[128:129], v[176:177]
	v_pk_mul_f32 v[178:179], v[124:125], v[172:173]
	v_mov_b32_e32 v159, v163
	v_pk_add_f32 v[162:163], v[124:125], v[172:173]
	v_mov_b32_e32 v177, v172
	v_mov_b32_e32 v163, v179
	v_pk_add_f32 v[158:159], v[158:159], v[162:163]
	v_mov_b32_e32 v129, v124
	v_pk_add_f32 v[126:127], v[126:127], v[158:159]
	v_pk_mul_f32 v[158:159], v[176:177], v[176:177]
	v_mov_b32_e32 v162, v123
	v_pk_fma_f32 v[158:159], v[128:129], v[128:129], v[158:159]
	v_mov_b32_e32 v163, v122
	v_pk_add_f32 v[158:159], v[158:159], v[158:159] op_sel_hi:[0,1]
	v_mov_b32_e32 v139, v159
	v_pk_add_f32 v[126:127], v[126:127], v[138:139]
	v_mov_b32_e32 v158, v160
	v_mov_b32_e32 v159, v174
	v_mov_b32_e32 v129, v176
	v_mov_b32_e32 v125, v172
	s_branch .LBB0_584

; __device__ __forceinline__ float row_rstd_q(const float* ssq, int row, int fq) {
;     const f32x4 a = ((const f32x4*)(ssq + (size_t)row * 16))[fq];
;     float s = (a[0] + a[1]) + (a[2] + a[3]);
;     s += __shfl_xor(s, 16); s += __shfl_xor(s, 32);
;     return 1.0f / sqrtf(s * (1.0f / 1024.0f) + 1e-6f);
; }
;     __device__ __forceinline__ void operator()(const f32x4 (&acc)[2][2][4][2], const Unit& u, int wr, int wc, int fr, int fq) const {
;     ...
;                 const int row = row0 + ai * 128 + m * 16; const float rs = row_rstd_q(ssq, row, fq); float s1 = 0.f, s2 = 0.f;
.LBB0_590:
	s_waitcnt lgkmcnt(1)
	v_or_b32_e32 v116, 16, v152
	s_waitcnt lgkmcnt(0)
	v_ashrrev_i32_e32 v117, 31, v116
	v_lshlrev_b64 v[114:115], 6, v[116:117]
	s_cmp_eq_u32 s101, 0
	s_cbranch_scc1 .Lmy_z1_miss
	v_mov_b32_e32 v118, v241
	s_branch .Lmy_z1_join
.Lmy_z1_miss:
	v_lshl_add_u64 v[118:119], v[140:141], 0, v[114:115]
	global_load_dwordx4 v[118:121], v[118:119], off
	s_waitcnt vmcnt(0)
	v_mov_b32_e32 v124, v119
	v_mov_b32_e32 v125, v120
	v_mov_b32_e32 v119, v121
	v_pk_add_f32 v[118:119], v[124:125], v[118:119]
	s_nop 0
	v_add_f32_e32 v117, v118, v119
	ds_bpermute_b32 v118, v153, v117
	s_waitcnt lgkmcnt(0)
	v_add_f32_e32 v117, v117, v118
	ds_bpermute_b32 v118, v171, v117
	s_waitcnt lgkmcnt(0)
	v_add_f32_e32 v117, v117, v118
	v_fmamk_f32 v117, v117, 0x3a800000, v169
	v_mul_f32_e32 v118, 0x4f800000, v117
	v_cmp_gt_f32_e32 vcc, s21, v117
	s_nop 1
	v_cndmask_b32_e32 v117, v117, v118, vcc
	v_sqrt_f32_e32 v118, v117
	s_nop 0
	v_add_u32_e32 v119, -1, v118
	v_add_u32_e32 v120, 1, v118
	v_fma_f32 v121, -v119, v118, v117
	v_fma_f32 v124, -v120, v118, v117
	v_cmp_ge_f32_e64 s[12:13], 0, v121
	s_nop 1
	v_cndmask_b32_e64 v118, v118, v119, s[12:13]
	v_cmp_lt_f32_e64 s[12:13], 0, v124
	s_nop 1
	v_cndmask_b32_e64 v118, v118, v120, s[12:13]
	v_mul_f32_e32 v119, 0x37800000, v118
	v_cndmask_b32_e32 v118, v118, v119, vcc
	v_cmp_class_f32_e32 vcc, v117, v170
	s_nop 1
	v_cndmask_b32_e32 v117, v118, v117, vcc
	v_div_scale_f32 v118, s[12:13], v117, v117, 1.0
	v_rcp_f32_e32 v119, v118
	v_div_scale_f32 v120, vcc, 1.0, v117, 1.0
	v_fma_f32 v121, -v118, v119, 1.0
	v_fmac_f32_e32 v119, v121, v119
	v_mul_f32_e32 v121, v120, v119
	v_fma_f32 v124, -v118, v121, v120
	v_fmac_f32_e32 v121, v124, v119
	v_fma_f32 v118, -v118, v121, v120
	v_div_fmas_f32 v118, v118, v119, v121
	v_div_fixup_f32 v118, v118, v117, 1.0
	v_mov_b32_e32 v241, v118
; __device__ __forceinline__ float frcp(float x) { return __builtin_amdgcn_rcpf(x); }
; __device__ __forceinline__ float gelu_erf(float v) {
;     const float av = fabsf(v), t = frcp(av * 0.2316418882f + 1.0f);
;     float qq = t * 0.5307027145f + (-0.7265760135f); qq = qq * t + 0.7107068705f; qq = qq * t + (-0.142248368f); qq = qq * t + 0.127414796f; qq = qq * t;
;     const float e = __builtin_amdgcn_exp2f((v * v) * (-0.72134752044f));
;     const float m = v * (qq * e);
;     return v < 0.f ? m : v - m;
; }
;     __device__ __forceinline__ void operator()(const f32x4 (&acc)[2][2][4][2], const Unit& u, int wr, int wc, int fr, int fq) const {
;     ...
;                     f32x4 v0 = acc[ai][bj][m][0] * rs, v1 = acc[ai][bj][m][1] * rs;
;                     if (isg) {
; #pragma unroll
;                         for (int j = 0; j < 4; ++j) { v0[j] = gelu_erf(v0[j]); v1[j] = gelu_erf(v1[j]); }
;                         s1 += ((v0[0] + v0[1]) + (v0[2] + v0[3])) + ((v1[0] + v1[1]) + (v1[2] + v1[3]));
;                         s2 += ((v0[0] * v0[0] + v0[1] * v0[1]) + (v0[2] * v0[2] + v0[3] * v0[3])) + ((v1[0] * v1[0] + v1[1] * v1[1]) + (v1[2] * v1[2] + v1[3] * v1[3]));
;                     }
.Lmy_z1_join:
	s_and_b64 vcc, exec, s[10:11]
	v_pk_mul_f32 v[120:121], v[112:113], v[118:119] op_sel_hi:[1,0]
	v_pk_mul_f32 v[124:125], v[110:111], v[118:119] op_sel_hi:[1,0]
	v_pk_mul_f32 v[108:109], v[108:109], v[118:119] op_sel_hi:[1,0]
	v_pk_mul_f32 v[106:107], v[106:107], v[118:119] op_sel_hi:[1,0]
	s_cbranch_vccnz .LBB0_592
	v_fma_f32 v110, |v124|, s0, 1.0
	v_rcp_f32_e32 v111, v110
	v_fma_f32 v110, |v106|, s0, 1.0
	v_rcp_f32_e32 v110, v110
	v_mul_f32_e32 v112, v124, v124
	v_mul_f32_e32 v112, 0xbf38aa3b, v112
	v_mul_f32_e32 v117, v106, v106
	v_exp_f32_e32 v113, v112
	v_fmamk_f32 v112, v110, 0x3f07dc22, v150
	v_mul_f32_e32 v117, 0xbf38aa3b, v117
	v_fmaak_f32 v112, v110, v112, 0x3f35f0e3
	v_exp_f32_e32 v117, v117
	v_fmaak_f32 v112, v110, v112, 0xbe11a98e
	v_fmaak_f32 v112, v110, v112, 0x3e027906
	v_mul_f32_e32 v110, v110, v112
	v_mul_f32_e32 v126, v117, v110
	v_fma_f32 v110, |v125|, s0, 1.0
	v_rcp_f32_e32 v110, v110
	v_mul_f32_e32 v112, v125, v125
	v_mul_f32_e32 v112, 0xbf38aa3b, v112
	v_exp_f32_e32 v112, v112
	v_pk_fma_f32 v[128:129], v[110:111], s[48:49], v[150:151] op_sel_hi:[1,0,0]
	v_fma_f32 v117, |v107|, s0, 1.0
	v_pk_fma_f32 v[128:129], v[110:111], v[128:129], s[56:57] op_sel_hi:[1,1,0]
	v_rcp_f32_e32 v117, v117
	v_pk_fma_f32 v[128:129], v[110:111], v[128:129], s[60:61] op_sel_hi:[1,1,0]
	v_fma_f32 v119, |v120|, s0, 1.0
	v_pk_fma_f32 v[128:129], v[110:111], v[128:129], s[62:63] op_sel_hi:[1,1,0]
	v_rcp_f32_e32 v119, v119
	v_pk_mul_f32 v[110:111], v[110:111], v[128:129]
	v_fma_f32 v127, |v108|, s0, 1.0
	v_pk_mul_f32 v[110:111], v[112:113], v[110:111]
	v_mul_f32_e32 v113, v107, v107
	v_fmamk_f32 v112, v117, 0x3f07dc22, v150
	v_mul_f32_e32 v113, 0xbf38aa3b, v113
	v_fmaak_f32 v112, v117, v112, 0x3f35f0e3
	v_exp_f32_e32 v113, v113
	v_fmaak_f32 v112, v117, v112, 0xbe11a98e
	v_fmaak_f32 v112, v117, v112, 0x3e027906
	v_mul_f32_e32 v112, v117, v112
	v_mul_f32_e32 v117, v120, v120
	v_mul_f32_e32 v112, v113, v112
	v_fmamk_f32 v113, v119, 0x3f07dc22, v150
	v_mul_f32_e32 v117, 0xbf38aa3b, v117
	v_fmaak_f32 v113, v119, v113, 0x3f35f0e3
	v_exp_f32_e32 v117, v117
	v_fmaak_f32 v113, v119, v113, 0xbe11a98e
	v_rcp_f32_e32 v127, v127
	v_fmaak_f32 v113, v119, v113, 0x3e027906
	v_mul_f32_e32 v113, v119, v113
	v_mul_f32_e32 v128, v117, v113
	v_mul_f32_e32 v117, v108, v108
	v_fmamk_f32 v113, v127, 0x3f07dc22, v150
	v_mul_f32_e32 v117, 0xbf38aa3b, v117
	v_fmaak_f32 v113, v127, v113, 0x3f35f0e3
	v_exp_f32_e32 v117, v117
	v_fma_f32 v119, |v121|, s0, 1.0
	v_fmaak_f32 v113, v127, v113, 0xbe11a98e
	v_rcp_f32_e32 v119, v119
	v_fmaak_f32 v113, v127, v113, 0x3e027906
	v_mul_f32_e32 v113, v127, v113
	v_mul_f32_e32 v154, v117, v113
	v_mul_f32_e32 v117, v121, v121
	v_fmamk_f32 v113, v119, 0x3f07dc22, v150
	v_mul_f32_e32 v117, 0xbf38aa3b, v117
	v_fmaak_f32 v113, v119, v113, 0x3f35f0e3
	v_exp_f32_e32 v117, v117
	v_fma_f32 v127, |v109|, s0, 1.0
	v_fmaak_f32 v113, v119, v113, 0xbe11a98e
	v_rcp_f32_e32 v127, v127
	v_fmaak_f32 v113, v119, v113, 0x3e027906
	v_mul_f32_e32 v113, v119, v113
	v_mul_f32_e32 v156, v117, v113
	v_mul_f32_e32 v117, v109, v109
	v_fmamk_f32 v113, v127, 0x3f07dc22, v150
	v_mul_f32_e32 v117, 0xbf38aa3b, v117
	v_fmaak_f32 v113, v127, v113, 0x3f35f0e3
	v_exp_f32_e32 v117, v117
	v_fmaak_f32 v113, v127, v113, 0xbe11a98e
	v_fmaak_f32 v113, v127, v113, 0x3e027906
	v_mul_f32_e32 v113, v127, v113
	v_pk_mul_f32 v[160:161], v[124:125], v[110:111] op_sel:[1,0] op_sel_hi:[0,1]
	v_mov_b32_e32 v157, v110
	v_mov_b32_e32 v129, v110
	v_pk_fma_f32 v[110:111], v[124:125], v[110:111], v[124:125] op_sel:[1,0,1] op_sel_hi:[0,1,0] neg_lo:[1,0,0] neg_hi:[1,0,0]
	v_cmp_gt_f32_e64 s[12:13], 0, v124
	v_mul_f32_e32 v158, v117, v113
	v_mov_b32_e32 v162, v121
	v_mov_b32_e32 v163, v125
	v_mov_b32_e32 v174, v120
	v_mov_b32_e32 v175, v125
	v_pk_mov_b32 v[182:183], v[106:107], v[120:121] op_sel:[1,0]
	v_mov_b32_e32 v113, v128
	v_cndmask_b32_e64 v161, v111, v161, s[12:13]
	v_cmp_gt_f32_e64 s[12:13], 0, v125
	v_pk_mul_f32 v[172:173], v[162:163], v[156:157]
	v_pk_mul_f32 v[176:177], v[174:175], v[128:129]
	v_mov_b32_e32 v178, v106
	v_mov_b32_e32 v179, v120
	v_mov_b32_e32 v127, v128
	v_pk_mul_f32 v[184:185], v[182:183], v[112:113]
	v_mov_b32_e32 v186, v108
	v_mov_b32_e32 v187, v121
	v_mov_b32_e32 v155, v156
	v_pk_fma_f32 v[128:129], v[174:175], v[128:129], v[174:175] neg_lo:[1,0,0] neg_hi:[1,0,0]
	v_mov_b32_e32 v159, v156
	v_pk_fma_f32 v[156:157], v[162:163], v[156:157], v[162:163] neg_lo:[1,0,0] neg_hi:[1,0,0]
	v_cndmask_b32_e64 v160, v110, v160, s[12:13]
	v_pk_fma_f32 v[110:111], v[182:183], v[112:113], v[182:183] neg_lo:[1,0,0] neg_hi:[1,0,0]
	v_cmp_gt_f32_e64 s[14:15], 0, v107
	v_pk_mul_f32 v[180:181], v[178:179], v[126:127]
	v_pk_mul_f32 v[188:189], v[186:187], v[154:155]
	v_pk_fma_f32 v[126:127], v[178:179], v[126:127], v[178:179] neg_lo:[1,0,0] neg_hi:[1,0,0]
	v_cmp_gt_f32_e32 vcc, 0, v120
	v_mov_b32_e32 v120, v109
	v_cmp_gt_f32_e64 s[16:17], 0, v106
	v_cndmask_b32_e64 v113, v129, v177, s[12:13]
	v_pk_fma_f32 v[124:125], v[186:187], v[154:155], v[186:187] neg_lo:[1,0,0] neg_hi:[1,0,0]
	v_cndmask_b32_e64 v129, v157, v173, s[12:13]
	v_cmp_gt_f32_e64 s[12:13], 0, v121
	v_cndmask_b32_e64 v154, v110, v184, s[14:15]
	v_mov_b32_e32 v110, v161
	v_pk_mul_f32 v[174:175], v[120:121], v[158:159]
	v_cndmask_b32_e32 v107, v127, v181, vcc
	v_cndmask_b32_e64 v106, v126, v180, s[16:17]
	v_cndmask_b32_e32 v112, v128, v176, vcc
	v_pk_fma_f32 v[126:127], v[120:121], v[158:159], v[120:121] neg_lo:[1,0,0] neg_hi:[1,0,0]
	v_cndmask_b32_e64 v128, v156, v172, s[12:13]
	v_cndmask_b32_e32 v155, v111, v185, vcc
	v_cmp_gt_f32_e32 vcc, 0, v108
	v_pk_add_f32 v[110:111], v[110:111], v[160:161] op_sel_hi:[0,1]
	v_pk_mul_f32 v[120:121], v[160:161], v[160:161]
	v_cmp_gt_f32_e64 s[16:17], 0, v109
	v_cndmask_b32_e64 v109, v125, v189, s[12:13]
	v_cndmask_b32_e32 v108, v124, v188, vcc
	v_mov_b32_e32 v111, v121
	v_pk_add_f32 v[120:121], v[112:113], v[128:129]
	v_pk_mul_f32 v[124:125], v[112:113], v[128:129]
	v_cndmask_b32_e64 v127, v127, v175, s[12:13]
	v_mov_b32_e32 v121, v125
	v_cndmask_b32_e64 v126, v126, v174, s[16:17]
	v_pk_add_f32 v[110:111], v[110:111], v[120:121]
	v_pk_add_f32 v[120:121], v[106:107], v[154:155]
	v_pk_mul_f32 v[124:125], v[106:107], v[154:155]
	v_pk_mul_f32 v[156:157], v[108:109], v[126:127]
	v_mov_b32_e32 v121, v125
	v_pk_add_f32 v[124:125], v[108:109], v[126:127]
	v_mov_b32_e32 v155, v126
	v_mov_b32_e32 v125, v157
	v_pk_add_f32 v[120:121], v[120:121], v[124:125]
	v_mov_b32_e32 v107, v108
	v_pk_add_f32 v[110:111], v[110:111], v[120:121]
	v_pk_mul_f32 v[120:121], v[154:155], v[154:155]
	v_mov_b32_e32 v124, v161
	v_pk_fma_f32 v[120:121], v[106:107], v[106:107], v[120:121]
	v_mov_b32_e32 v125, v160
	v_pk_add_f32 v[120:121], v[120:121], v[120:121] op_sel_hi:[0,1]
	v_mov_b32_e32 v139, v121
	v_pk_add_f32 v[110:111], v[110:111], v[138:139]
	v_mov_b32_e32 v120, v112
	v_mov_b32_e32 v121, v128
	v_mov_b32_e32 v107, v154
	v_mov_b32_e32 v109, v126
	s_branch .LBB0_593

; __device__ __forceinline__ float row_rstd_q(const float* ssq, int row, int fq) {
;     const f32x4 a = ((const f32x4*)(ssq + (size_t)row * 16))[fq];
;     float s = (a[0] + a[1]) + (a[2] + a[3]);
;     s += __shfl_xor(s, 16); s += __shfl_xor(s, 32);
;     return 1.0f / sqrtf(s * (1.0f / 1024.0f) + 1e-6f);
; }
;     __device__ __forceinline__ void operator()(const f32x4 (&acc)[2][2][4][2], const Unit& u, int wr, int wc, int fr, int fq) const {
;     ...
;                 const int row = row0 + ai * 128 + m * 16; const float rs = row_rstd_q(ssq, row, fq); float s1 = 0.f, s2 = 0.f;
.LBB0_599:
	s_waitcnt lgkmcnt(1)
	v_or_b32_e32 v100, 32, v152
	s_waitcnt lgkmcnt(0)
	v_ashrrev_i32_e32 v101, 31, v100
	v_lshlrev_b64 v[98:99], 6, v[100:101]
	s_cmp_eq_u32 s101, 0
	s_cbranch_scc1 .Lmy_z2_miss
	v_mov_b32_e32 v102, v242
	s_branch .Lmy_z2_join
.Lmy_z2_miss:
	v_lshl_add_u64 v[102:103], v[140:141], 0, v[98:99]
	global_load_dwordx4 v[102:105], v[102:103], off
	s_waitcnt vmcnt(0)
	v_mov_b32_e32 v106, v103
	v_mov_b32_e32 v107, v104
	v_mov_b32_e32 v103, v105
	v_pk_add_f32 v[102:103], v[106:107], v[102:103]
	s_nop 0
	v_add_f32_e32 v101, v102, v103
	ds_bpermute_b32 v102, v153, v101
	s_waitcnt lgkmcnt(0)
	v_add_f32_e32 v101, v101, v102
	ds_bpermute_b32 v102, v171, v101
	s_waitcnt lgkmcnt(0)
	v_add_f32_e32 v101, v101, v102
	v_fmamk_f32 v101, v101, 0x3a800000, v169
	v_mul_f32_e32 v102, 0x4f800000, v101
	v_cmp_gt_f32_e32 vcc, s21, v101
	s_nop 1
	v_cndmask_b32_e32 v101, v101, v102, vcc
	v_sqrt_f32_e32 v102, v101
	s_nop 0
	v_add_u32_e32 v103, -1, v102
	v_add_u32_e32 v104, 1, v102
	v_fma_f32 v105, -v103, v102, v101
	v_fma_f32 v106, -v104, v102, v101
	v_cmp_ge_f32_e64 s[14:15], 0, v105
	s_nop 1
	v_cndmask_b32_e64 v102, v102, v103, s[14:15]
	v_cmp_lt_f32_e64 s[14:15], 0, v106
	s_nop 1
	v_cndmask_b32_e64 v102, v102, v104, s[14:15]
	v_mul_f32_e32 v103, 0x37800000, v102
	v_cndmask_b32_e32 v102, v102, v103, vcc
	v_cmp_class_f32_e32 vcc, v101, v170
	s_nop 1
	v_cndmask_b32_e32 v101, v102, v101, vcc
	v_div_scale_f32 v102, s[14:15], v101, v101, 1.0
	v_rcp_f32_e32 v103, v102
	v_div_scale_f32 v104, vcc, 1.0, v101, 1.0
	v_fma_f32 v105, -v102, v103, 1.0
	v_fmac_f32_e32 v103, v105, v103
	v_mul_f32_e32 v105, v104, v103
	v_fma_f32 v106, -v102, v105, v104
	v_fmac_f32_e32 v105, v106, v103
	v_fma_f32 v102, -v102, v105, v104
	v_div_fmas_f32 v102, v102, v103, v105
	v_div_fixup_f32 v102, v102, v101, 1.0
	v_mov_b32_e32 v242, v102
; __device__ __forceinline__ float frcp(float x) { return __builtin_amdgcn_rcpf(x); }
; __device__ __forceinline__ float gelu_erf(float v) {
;     const float av = fabsf(v), t = frcp(av * 0.2316418882f + 1.0f);
;     float qq = t * 0.5307027145f + (-0.7265760135f); qq = qq * t + 0.7107068705f; qq = qq * t + (-0.142248368f); qq = qq * t + 0.127414796f; qq = qq * t;
;     const float e = __builtin_amdgcn_exp2f((v * v) * (-0.72134752044f));
;     const float m = v * (qq * e);
;     return v < 0.f ? m : v - m;
; }
;     __device__ __forceinline__ void operator()(const f32x4 (&acc)[2][2][4][2], const Unit& u, int wr, int wc, int fr, int fq) const {
;     ...
;                     f32x4 v0 = acc[ai][bj][m][0] * rs, v1 = acc[ai][bj][m][1] * rs;
;                     if (isg) {
; #pragma unroll
;                         for (int j = 0; j < 4; ++j) { v0[j] = gelu_erf(v0[j]); v1[j] = gelu_erf(v1[j]); }
;                         s1 += ((v0[0] + v0[1]) + (v0[2] + v0[3])) + ((v1[0] + v1[1]) + (v1[2] + v1[3]));
;                         s2 += ((v0[0] * v0[0] + v0[1] * v0[1]) + (v0[2] * v0[2] + v0[3] * v0[3])) + ((v1[0] * v1[0] + v1[1] * v1[1]) + (v1[2] * v1[2] + v1[3] * v1[3]));
;                     }
.Lmy_z2_join:
	s_and_b64 vcc, exec, s[10:11]
	v_pk_mul_f32 v[104:105], v[96:97], v[102:103] op_sel_hi:[1,0]
	v_pk_mul_f32 v[106:107], v[94:95], v[102:103] op_sel_hi:[1,0]
	v_pk_mul_f32 v[92:93], v[92:93], v[102:103] op_sel_hi:[1,0]
	v_pk_mul_f32 v[90:91], v[90:91], v[102:103] op_sel_hi:[1,0]
	s_cbranch_vccnz .LBB0_601
	v_fma_f32 v94, |v106|, s0, 1.0
	v_rcp_f32_e32 v95, v94
	v_fma_f32 v94, |v90|, s0, 1.0
	v_rcp_f32_e32 v94, v94
	v_mul_f32_e32 v96, v106, v106
	v_mul_f32_e32 v96, 0xbf38aa3b, v96
	v_mul_f32_e32 v101, v90, v90
	v_exp_f32_e32 v97, v96
	v_fmamk_f32 v96, v94, 0x3f07dc22, v150
	v_mul_f32_e32 v101, 0xbf38aa3b, v101
	v_fmaak_f32 v96, v94, v96, 0x3f35f0e3
	v_exp_f32_e32 v101, v101
	v_fmaak_f32 v96, v94, v96, 0xbe11a98e
	v_fmaak_f32 v96, v94, v96, 0x3e027906
	v_mul_f32_e32 v94, v94, v96
	v_mul_f32_e32 v108, v101, v94
	v_fma_f32 v94, |v107|, s0, 1.0
	v_rcp_f32_e32 v94, v94
	v_mul_f32_e32 v96, v107, v107
	v_mul_f32_e32 v96, 0xbf38aa3b, v96
	v_exp_f32_e32 v96, v96
	v_pk_fma_f32 v[110:111], v[94:95], s[48:49], v[150:151] op_sel_hi:[1,0,0]
	v_fma_f32 v101, |v91|, s0, 1.0
	v_pk_fma_f32 v[110:111], v[94:95], v[110:111], s[56:57] op_sel_hi:[1,1,0]
	v_rcp_f32_e32 v101, v101
	v_pk_fma_f32 v[110:111], v[94:95], v[110:111], s[60:61] op_sel_hi:[1,1,0]
	v_fma_f32 v103, |v104|, s0, 1.0
	v_pk_fma_f32 v[110:111], v[94:95], v[110:111], s[62:63] op_sel_hi:[1,1,0]
	v_rcp_f32_e32 v103, v103
	v_pk_mul_f32 v[94:95], v[94:95], v[110:111]
	v_fma_f32 v109, |v92|, s0, 1.0
	v_pk_mul_f32 v[94:95], v[96:97], v[94:95]
	v_mul_f32_e32 v97, v91, v91
	v_fmamk_f32 v96, v101, 0x3f07dc22, v150
	v_mul_f32_e32 v97, 0xbf38aa3b, v97
	v_fmaak_f32 v96, v101, v96, 0x3f35f0e3
	v_exp_f32_e32 v97, v97
	v_fmaak_f32 v96, v101, v96, 0xbe11a98e
	v_fmaak_f32 v96, v101, v96, 0x3e027906
	v_mul_f32_e32 v96, v101, v96
	v_mul_f32_e32 v101, v104, v104
	v_mul_f32_e32 v96, v97, v96
	v_fmamk_f32 v97, v103, 0x3f07dc22, v150
	v_mul_f32_e32 v101, 0xbf38aa3b, v101
	v_fmaak_f32 v97, v103, v97, 0x3f35f0e3
	v_exp_f32_e32 v101, v101
	v_fmaak_f32 v97, v103, v97, 0xbe11a98e
	v_rcp_f32_e32 v109, v109
	v_fmaak_f32 v97, v103, v97, 0x3e027906
	v_mul_f32_e32 v97, v103, v97
	v_mul_f32_e32 v110, v101, v97
	v_mul_f32_e32 v101, v92, v92
	v_fmamk_f32 v97, v109, 0x3f07dc22, v150
	v_mul_f32_e32 v101, 0xbf38aa3b, v101
	v_fmaak_f32 v97, v109, v97, 0x3f35f0e3
	v_exp_f32_e32 v101, v101
	v_fma_f32 v103, |v105|, s0, 1.0
	v_fmaak_f32 v97, v109, v97, 0xbe11a98e
	v_rcp_f32_e32 v103, v103
	v_fmaak_f32 v97, v109, v97, 0x3e027906
	v_mul_f32_e32 v97, v109, v97
	v_mul_f32_e32 v112, v101, v97
	v_mul_f32_e32 v101, v105, v105
	v_fmamk_f32 v97, v103, 0x3f07dc22, v150
	v_mul_f32_e32 v101, 0xbf38aa3b, v101
	v_fmaak_f32 v97, v103, v97, 0x3f35f0e3
	v_exp_f32_e32 v101, v101
	v_fma_f32 v109, |v93|, s0, 1.0
	v_fmaak_f32 v97, v103, v97, 0xbe11a98e
	v_rcp_f32_e32 v109, v109
	v_fmaak_f32 v97, v103, v97, 0x3e027906
	v_mul_f32_e32 v97, v103, v97
	v_mul_f32_e32 v114, v101, v97
	v_mul_f32_e32 v101, v93, v93
	v_fmamk_f32 v97, v109, 0x3f07dc22, v150
	v_mul_f32_e32 v101, 0xbf38aa3b, v101
	v_fmaak_f32 v97, v109, v97, 0x3f35f0e3
	v_exp_f32_e32 v101, v101
	v_fmaak_f32 v97, v109, v97, 0xbe11a98e
	v_fmaak_f32 v97, v109, v97, 0x3e027906
	v_mul_f32_e32 v97, v109, v97
	v_pk_mul_f32 v[118:119], v[106:107], v[94:95] op_sel:[1,0] op_sel_hi:[0,1]
	v_mov_b32_e32 v115, v94
	v_mov_b32_e32 v111, v94
	v_pk_fma_f32 v[94:95], v[106:107], v[94:95], v[106:107] op_sel:[1,0,1] op_sel_hi:[0,1,0] neg_lo:[1,0,0] neg_hi:[1,0,0]
	v_cmp_gt_f32_e64 s[14:15], 0, v106
	v_mul_f32_e32 v116, v101, v97
	v_mov_b32_e32 v120, v105
	v_mov_b32_e32 v121, v107
	v_mov_b32_e32 v126, v104
	v_mov_b32_e32 v127, v107
	v_pk_mov_b32 v[158:159], v[90:91], v[104:105] op_sel:[1,0]
	v_mov_b32_e32 v97, v110
	v_cndmask_b32_e64 v119, v95, v119, s[14:15]
	v_cmp_gt_f32_e64 s[14:15], 0, v107
	v_pk_mul_f32 v[124:125], v[120:121], v[114:115]
	v_pk_mul_f32 v[128:129], v[126:127], v[110:111]
	v_mov_b32_e32 v154, v90
	v_mov_b32_e32 v155, v104
	v_mov_b32_e32 v109, v110
	v_pk_mul_f32 v[160:161], v[158:159], v[96:97]
	v_mov_b32_e32 v162, v92
	v_mov_b32_e32 v163, v105
	v_mov_b32_e32 v113, v114
	v_pk_fma_f32 v[110:111], v[126:127], v[110:111], v[126:127] neg_lo:[1,0,0] neg_hi:[1,0,0]
	v_mov_b32_e32 v117, v114
	v_pk_fma_f32 v[114:115], v[120:121], v[114:115], v[120:121] neg_lo:[1,0,0] neg_hi:[1,0,0]
	v_cndmask_b32_e64 v118, v94, v118, s[14:15]
	v_pk_fma_f32 v[94:95], v[158:159], v[96:97], v[158:159] neg_lo:[1,0,0] neg_hi:[1,0,0]
	v_cmp_gt_f32_e64 s[16:17], 0, v91
	v_pk_mul_f32 v[156:157], v[154:155], v[108:109]
	v_pk_mul_f32 v[172:173], v[162:163], v[112:113]
	v_pk_fma_f32 v[108:109], v[154:155], v[108:109], v[154:155] neg_lo:[1,0,0] neg_hi:[1,0,0]
	v_cmp_gt_f32_e32 vcc, 0, v104
	v_mov_b32_e32 v104, v93
	v_cmp_gt_f32_e64 s[18:19], 0, v90
	v_cndmask_b32_e64 v97, v111, v129, s[14:15]
	v_pk_fma_f32 v[106:107], v[162:163], v[112:113], v[162:163] neg_lo:[1,0,0] neg_hi:[1,0,0]
	v_cndmask_b32_e64 v111, v115, v125, s[14:15]
	v_cmp_gt_f32_e64 s[14:15], 0, v105
	v_cndmask_b32_e64 v112, v94, v160, s[16:17]
	v_mov_b32_e32 v94, v119
	v_pk_mul_f32 v[126:127], v[104:105], v[116:117]
	v_cndmask_b32_e32 v91, v109, v157, vcc
	v_cndmask_b32_e64 v90, v108, v156, s[18:19]
	v_cndmask_b32_e32 v96, v110, v128, vcc
	v_pk_fma_f32 v[108:109], v[104:105], v[116:117], v[104:105] neg_lo:[1,0,0] neg_hi:[1,0,0]
	v_cndmask_b32_e64 v110, v114, v124, s[14:15]
	v_cndmask_b32_e32 v113, v95, v161, vcc
	v_cmp_gt_f32_e32 vcc, 0, v92
	v_pk_add_f32 v[94:95], v[94:95], v[118:119] op_sel_hi:[0,1]
	v_pk_mul_f32 v[104:105], v[118:119], v[118:119]
	v_cmp_gt_f32_e64 s[18:19], 0, v93
	v_cndmask_b32_e64 v93, v107, v173, s[14:15]
	v_cndmask_b32_e32 v92, v106, v172, vcc
	v_mov_b32_e32 v95, v105
	v_pk_add_f32 v[104:105], v[96:97], v[110:111]
	v_pk_mul_f32 v[106:107], v[96:97], v[110:111]
	v_cndmask_b32_e64 v109, v109, v127, s[14:15]
	v_mov_b32_e32 v105, v107
	v_cndmask_b32_e64 v108, v108, v126, s[18:19]
	v_pk_add_f32 v[94:95], v[94:95], v[104:105]
	v_pk_add_f32 v[104:105], v[90:91], v[112:113]
	v_pk_mul_f32 v[106:107], v[90:91], v[112:113]
	v_pk_mul_f32 v[114:115], v[92:93], v[108:109]
	v_mov_b32_e32 v105, v107
	v_pk_add_f32 v[106:107], v[92:93], v[108:109]
	v_mov_b32_e32 v113, v108
	v_mov_b32_e32 v107, v115
	v_pk_add_f32 v[104:105], v[104:105], v[106:107]
	v_mov_b32_e32 v91, v92
	v_pk_add_f32 v[94:95], v[94:95], v[104:105]
	v_pk_mul_f32 v[104:105], v[112:113], v[112:113]
	v_mov_b32_e32 v106, v119
	v_pk_fma_f32 v[104:105], v[90:91], v[90:91], v[104:105]
	v_mov_b32_e32 v107, v118
	v_pk_add_f32 v[104:105], v[104:105], v[104:105] op_sel_hi:[0,1]
	v_mov_b32_e32 v139, v105
	v_pk_add_f32 v[94:95], v[94:95], v[138:139]
	v_mov_b32_e32 v104, v96
	v_mov_b32_e32 v105, v110
	v_mov_b32_e32 v91, v112
	v_mov_b32_e32 v93, v108
	s_branch .LBB0_602

; __device__ __forceinline__ float row_rstd_q(const float* ssq, int row, int fq) {
;     const f32x4 a = ((const f32x4*)(ssq + (size_t)row * 16))[fq];
;     float s = (a[0] + a[1]) + (a[2] + a[3]);
;     s += __shfl_xor(s, 16); s += __shfl_xor(s, 32);
;     return 1.0f / sqrtf(s * (1.0f / 1024.0f) + 1e-6f);
; }
;     __device__ __forceinline__ void operator()(const f32x4 (&acc)[2][2][4][2], const Unit& u, int wr, int wc, int fr, int fq) const {
;     ...
;                 const int row = row0 + ai * 128 + m * 16; const float rs = row_rstd_q(ssq, row, fq); float s1 = 0.f, s2 = 0.f;
.LBB0_608:
	s_waitcnt lgkmcnt(1)
	v_or_b32_e32 v84, 48, v152
	s_waitcnt lgkmcnt(0)
	v_ashrrev_i32_e32 v85, 31, v84
	v_lshlrev_b64 v[82:83], 6, v[84:85]
	s_cmp_eq_u32 s101, 0
	s_cbranch_scc1 .Lmy_z3_miss
	v_mov_b32_e32 v86, v243
	s_branch .Lmy_z3_join
.Lmy_z3_miss:
	v_lshl_add_u64 v[86:87], v[140:141], 0, v[82:83]
	global_load_dwordx4 v[86:89], v[86:87], off
	s_waitcnt vmcnt(0)
	v_mov_b32_e32 v90, v87
	v_mov_b32_e32 v91, v88
	v_mov_b32_e32 v87, v89
	v_pk_add_f32 v[86:87], v[90:91], v[86:87]
	s_nop 0
	v_add_f32_e32 v85, v86, v87
	ds_bpermute_b32 v86, v153, v85
	s_waitcnt lgkmcnt(0)
	v_add_f32_e32 v85, v85, v86
	ds_bpermute_b32 v86, v171, v85
	s_waitcnt lgkmcnt(0)
	v_add_f32_e32 v85, v85, v86
	v_fmamk_f32 v85, v85, 0x3a800000, v169
	v_mul_f32_e32 v86, 0x4f800000, v85
	v_cmp_gt_f32_e32 vcc, s21, v85
	s_nop 1
	v_cndmask_b32_e32 v85, v85, v86, vcc
	v_sqrt_f32_e32 v86, v85
	s_nop 0
	v_add_u32_e32 v87, -1, v86
	v_add_u32_e32 v88, 1, v86
	v_fma_f32 v89, -v87, v86, v85
	v_fma_f32 v90, -v88, v86, v85
	v_cmp_ge_f32_e64 s[14:15], 0, v89
	s_nop 1
	v_cndmask_b32_e64 v86, v86, v87, s[14:15]
	v_cmp_lt_f32_e64 s[14:15], 0, v90
	s_nop 1
	v_cndmask_b32_e64 v86, v86, v88, s[14:15]
	v_mul_f32_e32 v87, 0x37800000, v86
	v_cndmask_b32_e32 v86, v86, v87, vcc
	v_cmp_class_f32_e32 vcc, v85, v170
	s_nop 1
	v_cndmask_b32_e32 v85, v86, v85, vcc
	v_div_scale_f32 v86, s[14:15], v85, v85, 1.0
	v_rcp_f32_e32 v87, v86
	v_div_scale_f32 v88, vcc, 1.0, v85, 1.0
	v_fma_f32 v89, -v86, v87, 1.0
	v_fmac_f32_e32 v87, v89, v87
	v_mul_f32_e32 v89, v88, v87
	v_fma_f32 v90, -v86, v89, v88
	v_fmac_f32_e32 v89, v90, v87
	v_fma_f32 v86, -v86, v89, v88
	v_div_fmas_f32 v86, v86, v87, v89
	v_div_fixup_f32 v86, v86, v85, 1.0
	v_mov_b32_e32 v243, v86
; __device__ __forceinline__ float frcp(float x) { return __builtin_amdgcn_rcpf(x); }
; __device__ __forceinline__ float gelu_erf(float v) {
;     const float av = fabsf(v), t = frcp(av * 0.2316418882f + 1.0f);
;     float qq = t * 0.5307027145f + (-0.7265760135f); qq = qq * t + 0.7107068705f; qq = qq * t + (-0.142248368f); qq = qq * t + 0.127414796f; qq = qq * t;
;     const float e = __builtin_amdgcn_exp2f((v * v) * (-0.72134752044f));
;     const float m = v * (qq * e);
;     return v < 0.f ? m : v - m;
; }
;     __device__ __forceinline__ void operator()(const f32x4 (&acc)[2][2][4][2], const Unit& u, int wr, int wc, int fr, int fq) const {
;     ...
;                     f32x4 v0 = acc[ai][bj][m][0] * rs, v1 = acc[ai][bj][m][1] * rs;
;                     if (isg) {
; #pragma unroll
;                         for (int j = 0; j < 4; ++j) { v0[j] = gelu_erf(v0[j]); v1[j] = gelu_erf(v1[j]); }
;                         s1 += ((v0[0] + v0[1]) + (v0[2] + v0[3])) + ((v1[0] + v1[1]) + (v1[2] + v1[3]));
;                         s2 += ((v0[0] * v0[0] + v0[1] * v0[1]) + (v0[2] * v0[2] + v0[3] * v0[3])) + ((v1[0] * v1[0] + v1[1] * v1[1]) + (v1[2] * v1[2] + v1[3] * v1[3]));
;                     }
.Lmy_z3_join:
	s_and_b64 vcc, exec, s[10:11]
	v_pk_mul_f32 v[88:89], v[80:81], v[86:87] op_sel_hi:[1,0]
	v_pk_mul_f32 v[90:91], v[78:79], v[86:87] op_sel_hi:[1,0]
	v_pk_mul_f32 v[76:77], v[76:77], v[86:87] op_sel_hi:[1,0]
	v_pk_mul_f32 v[74:75], v[74:75], v[86:87] op_sel_hi:[1,0]
	s_cbranch_vccnz .LBB0_610
	v_fma_f32 v78, |v90|, s0, 1.0
	v_rcp_f32_e32 v79, v78
	v_fma_f32 v78, |v74|, s0, 1.0
	v_rcp_f32_e32 v78, v78
	v_mul_f32_e32 v80, v90, v90
	v_mul_f32_e32 v80, 0xbf38aa3b, v80
	v_mul_f32_e32 v85, v74, v74
	v_exp_f32_e32 v81, v80
	v_fmamk_f32 v80, v78, 0x3f07dc22, v150
	v_mul_f32_e32 v85, 0xbf38aa3b, v85
	v_fmaak_f32 v80, v78, v80, 0x3f35f0e3
	v_exp_f32_e32 v85, v85
	v_fmaak_f32 v80, v78, v80, 0xbe11a98e
	v_fmaak_f32 v80, v78, v80, 0x3e027906
	v_mul_f32_e32 v78, v78, v80
	v_mul_f32_e32 v92, v85, v78
	v_fma_f32 v78, |v91|, s0, 1.0
	v_rcp_f32_e32 v78, v78
	v_mul_f32_e32 v80, v91, v91
	v_mul_f32_e32 v80, 0xbf38aa3b, v80
	v_exp_f32_e32 v80, v80
	v_pk_fma_f32 v[94:95], v[78:79], s[48:49], v[150:151] op_sel_hi:[1,0,0]
	v_fma_f32 v85, |v75|, s0, 1.0
	v_pk_fma_f32 v[94:95], v[78:79], v[94:95], s[56:57] op_sel_hi:[1,1,0]
	v_rcp_f32_e32 v85, v85
	v_pk_fma_f32 v[94:95], v[78:79], v[94:95], s[60:61] op_sel_hi:[1,1,0]
	v_fma_f32 v87, |v88|, s0, 1.0
	v_pk_fma_f32 v[94:95], v[78:79], v[94:95], s[62:63] op_sel_hi:[1,1,0]
	v_rcp_f32_e32 v87, v87
	v_pk_mul_f32 v[78:79], v[78:79], v[94:95]
	v_fma_f32 v93, |v76|, s0, 1.0
	v_pk_mul_f32 v[78:79], v[80:81], v[78:79]
	v_mul_f32_e32 v81, v75, v75
	v_fmamk_f32 v80, v85, 0x3f07dc22, v150
	v_mul_f32_e32 v81, 0xbf38aa3b, v81
	v_fmaak_f32 v80, v85, v80, 0x3f35f0e3
	v_exp_f32_e32 v81, v81
	v_fmaak_f32 v80, v85, v80, 0xbe11a98e
	v_fmaak_f32 v80, v85, v80, 0x3e027906
	v_mul_f32_e32 v80, v85, v80
	v_mul_f32_e32 v85, v88, v88
	v_mul_f32_e32 v80, v81, v80
	v_fmamk_f32 v81, v87, 0x3f07dc22, v150
	v_mul_f32_e32 v85, 0xbf38aa3b, v85
	v_fmaak_f32 v81, v87, v81, 0x3f35f0e3
	v_exp_f32_e32 v85, v85
	v_fmaak_f32 v81, v87, v81, 0xbe11a98e
	v_rcp_f32_e32 v93, v93
	v_fmaak_f32 v81, v87, v81, 0x3e027906
	v_mul_f32_e32 v81, v87, v81
	v_mul_f32_e32 v94, v85, v81
	v_mul_f32_e32 v85, v76, v76
	v_fmamk_f32 v81, v93, 0x3f07dc22, v150
	v_mul_f32_e32 v85, 0xbf38aa3b, v85
	v_fmaak_f32 v81, v93, v81, 0x3f35f0e3
	v_exp_f32_e32 v85, v85
	v_fma_f32 v87, |v89|, s0, 1.0
	v_fmaak_f32 v81, v93, v81, 0xbe11a98e
	v_rcp_f32_e32 v87, v87
	v_fmaak_f32 v81, v93, v81, 0x3e027906
	v_mul_f32_e32 v81, v93, v81
	v_mul_f32_e32 v96, v85, v81
	v_mul_f32_e32 v85, v89, v89
	v_fmamk_f32 v81, v87, 0x3f07dc22, v150
	v_mul_f32_e32 v85, 0xbf38aa3b, v85
	v_fmaak_f32 v81, v87, v81, 0x3f35f0e3
	v_exp_f32_e32 v85, v85
	v_fma_f32 v93, |v77|, s0, 1.0
	v_fmaak_f32 v81, v87, v81, 0xbe11a98e
	v_rcp_f32_e32 v93, v93
	v_fmaak_f32 v81, v87, v81, 0x3e027906
	v_mul_f32_e32 v81, v87, v81
	v_mul_f32_e32 v98, v85, v81
	v_mul_f32_e32 v85, v77, v77
	v_fmamk_f32 v81, v93, 0x3f07dc22, v150
	v_mul_f32_e32 v85, 0xbf38aa3b, v85
	v_fmaak_f32 v81, v93, v81, 0x3f35f0e3
	v_exp_f32_e32 v85, v85
	v_fmaak_f32 v81, v93, v81, 0xbe11a98e
	v_fmaak_f32 v81, v93, v81, 0x3e027906
	v_mul_f32_e32 v81, v93, v81
	v_pk_mul_f32 v[102:103], v[90:91], v[78:79] op_sel:[1,0] op_sel_hi:[0,1]
	v_mov_b32_e32 v99, v78
	v_mov_b32_e32 v95, v78
	v_pk_fma_f32 v[78:79], v[90:91], v[78:79], v[90:91] op_sel:[1,0,1] op_sel_hi:[0,1,0] neg_lo:[1,0,0] neg_hi:[1,0,0]
	v_cmp_gt_f32_e64 s[14:15], 0, v90
	v_mul_f32_e32 v100, v85, v81
	v_mov_b32_e32 v104, v89
	v_mov_b32_e32 v105, v91
	v_mov_b32_e32 v108, v88
	v_mov_b32_e32 v109, v91
	v_pk_mov_b32 v[116:117], v[74:75], v[88:89] op_sel:[1,0]
	v_mov_b32_e32 v81, v94
	v_cndmask_b32_e64 v103, v79, v103, s[14:15]
	v_cmp_gt_f32_e64 s[14:15], 0, v91
	v_pk_mul_f32 v[106:107], v[104:105], v[98:99]
	v_pk_mul_f32 v[110:111], v[108:109], v[94:95]
	v_mov_b32_e32 v112, v74
	v_mov_b32_e32 v113, v88
	v_mov_b32_e32 v93, v94
	v_pk_mul_f32 v[118:119], v[116:117], v[80:81]
	v_mov_b32_e32 v120, v76
	v_mov_b32_e32 v121, v89
	v_mov_b32_e32 v97, v98
	v_pk_fma_f32 v[94:95], v[108:109], v[94:95], v[108:109] neg_lo:[1,0,0] neg_hi:[1,0,0]
	v_mov_b32_e32 v101, v98
	v_pk_fma_f32 v[98:99], v[104:105], v[98:99], v[104:105] neg_lo:[1,0,0] neg_hi:[1,0,0]
	v_cndmask_b32_e64 v102, v78, v102, s[14:15]
	v_pk_fma_f32 v[78:79], v[116:117], v[80:81], v[116:117] neg_lo:[1,0,0] neg_hi:[1,0,0]
	v_cmp_gt_f32_e64 s[16:17], 0, v75
	v_pk_mul_f32 v[114:115], v[112:113], v[92:93]
	v_pk_mul_f32 v[124:125], v[120:121], v[96:97]
	v_pk_fma_f32 v[92:93], v[112:113], v[92:93], v[112:113] neg_lo:[1,0,0] neg_hi:[1,0,0]
	v_cmp_gt_f32_e32 vcc, 0, v88
	v_mov_b32_e32 v88, v77
	v_cmp_gt_f32_e64 s[18:19], 0, v74
	v_cndmask_b32_e64 v81, v95, v111, s[14:15]
	v_pk_fma_f32 v[90:91], v[120:121], v[96:97], v[120:121] neg_lo:[1,0,0] neg_hi:[1,0,0]
	v_cndmask_b32_e64 v95, v99, v107, s[14:15]
	v_cmp_gt_f32_e64 s[14:15], 0, v89
	v_cndmask_b32_e64 v96, v78, v118, s[16:17]
	v_mov_b32_e32 v78, v103
	v_pk_mul_f32 v[108:109], v[88:89], v[100:101]
	v_cndmask_b32_e32 v75, v93, v115, vcc
	v_cndmask_b32_e64 v74, v92, v114, s[18:19]
	v_cndmask_b32_e32 v80, v94, v110, vcc
	v_pk_fma_f32 v[92:93], v[88:89], v[100:101], v[88:89] neg_lo:[1,0,0] neg_hi:[1,0,0]
	v_cndmask_b32_e64 v94, v98, v106, s[14:15]
	v_cndmask_b32_e32 v97, v79, v119, vcc
	v_cmp_gt_f32_e32 vcc, 0, v76
	v_pk_add_f32 v[78:79], v[78:79], v[102:103] op_sel_hi:[0,1]
	v_pk_mul_f32 v[88:89], v[102:103], v[102:103]
	v_cmp_gt_f32_e64 s[18:19], 0, v77
	v_cndmask_b32_e64 v77, v91, v125, s[14:15]
	v_cndmask_b32_e32 v76, v90, v124, vcc
	v_mov_b32_e32 v79, v89
	v_pk_add_f32 v[88:89], v[80:81], v[94:95]
	v_pk_mul_f32 v[90:91], v[80:81], v[94:95]
	v_cndmask_b32_e64 v93, v93, v109, s[14:15]
	v_mov_b32_e32 v89, v91
	v_cndmask_b32_e64 v92, v92, v108, s[18:19]
	v_pk_add_f32 v[78:79], v[78:79], v[88:89]
	v_pk_add_f32 v[88:89], v[74:75], v[96:97]
	v_pk_mul_f32 v[90:91], v[74:75], v[96:97]
	v_pk_mul_f32 v[98:99], v[76:77], v[92:93]
	v_mov_b32_e32 v89, v91
	v_pk_add_f32 v[90:91], v[76:77], v[92:93]
	v_mov_b32_e32 v97, v92
	v_mov_b32_e32 v91, v99
	v_pk_add_f32 v[88:89], v[88:89], v[90:91]
	v_mov_b32_e32 v75, v76
	v_pk_add_f32 v[78:79], v[78:79], v[88:89]
	v_pk_mul_f32 v[88:89], v[96:97], v[96:97]
	v_mov_b32_e32 v90, v103
	v_pk_fma_f32 v[88:89], v[74:75], v[74:75], v[88:89]
	v_mov_b32_e32 v91, v102
	v_pk_add_f32 v[88:89], v[88:89], v[88:89] op_sel_hi:[0,1]
	v_mov_b32_e32 v139, v89
	v_pk_add_f32 v[78:79], v[78:79], v[138:139]
	v_mov_b32_e32 v88, v80
	v_mov_b32_e32 v89, v94
	v_mov_b32_e32 v75, v96
	v_mov_b32_e32 v77, v92
	s_branch .LBB0_611

; __device__ __forceinline__ float row_rstd_q(const float* ssq, int row, int fq) {
;     const f32x4 a = ((const f32x4*)(ssq + (size_t)row * 16))[fq];
;     float s = (a[0] + a[1]) + (a[2] + a[3]);
;     s += __shfl_xor(s, 16); s += __shfl_xor(s, 32);
;     return 1.0f / sqrtf(s * (1.0f / 1024.0f) + 1e-6f);
; }
;     __device__ __forceinline__ void operator()(const f32x4 (&acc)[2][2][4][2], const Unit& u, int wr, int wc, int fr, int fq) const {
;     ...
;                 const int row = row0 + ai * 128 + m * 16; const float rs = row_rstd_q(ssq, row, fq); float s1 = 0.f, s2 = 0.f;
.LBB0_617:
	s_waitcnt lgkmcnt(1)
	v_add_u32_e32 v68, 0x80, v152
	s_waitcnt lgkmcnt(0)
	v_ashrrev_i32_e32 v69, 31, v68
	v_lshlrev_b64 v[66:67], 6, v[68:69]
	s_cmp_eq_u32 s101, 0
	s_cbranch_scc1 .Lmy_z4_miss
	v_mov_b32_e32 v70, v244
	s_branch .Lmy_z4_join
.Lmy_z4_miss:
	v_lshl_add_u64 v[70:71], v[140:141], 0, v[66:67]
	global_load_dwordx4 v[70:73], v[70:71], off
	s_waitcnt vmcnt(0)
	v_mov_b32_e32 v74, v71
	v_mov_b32_e32 v75, v72
	v_mov_b32_e32 v71, v73
	v_pk_add_f32 v[70:71], v[74:75], v[70:71]
	s_nop 0
	v_add_f32_e32 v69, v70, v71
	ds_bpermute_b32 v70, v153, v69
	s_waitcnt lgkmcnt(0)
	v_add_f32_e32 v69, v69, v70
	ds_bpermute_b32 v70, v171, v69
	s_waitcnt lgkmcnt(0)
	v_add_f32_e32 v69, v69, v70
	v_fmamk_f32 v69, v69, 0x3a800000, v169
	v_mul_f32_e32 v70, 0x4f800000, v69
	v_cmp_gt_f32_e32 vcc, s21, v69
	s_nop 1
	v_cndmask_b32_e32 v69, v69, v70, vcc
	v_sqrt_f32_e32 v70, v69
	s_nop 0
	v_add_u32_e32 v71, -1, v70
	v_add_u32_e32 v72, 1, v70
	v_fma_f32 v73, -v71, v70, v69
	v_fma_f32 v74, -v72, v70, v69
	v_cmp_ge_f32_e64 s[14:15], 0, v73
	s_nop 1
	v_cndmask_b32_e64 v70, v70, v71, s[14:15]
	v_cmp_lt_f32_e64 s[14:15], 0, v74
	s_nop 1
	v_cndmask_b32_e64 v70, v70, v72, s[14:15]
	v_mul_f32_e32 v71, 0x37800000, v70
	v_cndmask_b32_e32 v70, v70, v71, vcc
	v_cmp_class_f32_e32 vcc, v69, v170
	s_nop 1
	v_cndmask_b32_e32 v69, v70, v69, vcc
	v_div_scale_f32 v70, s[14:15], v69, v69, 1.0
	v_rcp_f32_e32 v71, v70
	v_div_scale_f32 v72, vcc, 1.0, v69, 1.0
	v_fma_f32 v73, -v70, v71, 1.0
	v_fmac_f32_e32 v71, v73, v71
	v_mul_f32_e32 v73, v72, v71
	v_fma_f32 v74, -v70, v73, v72
	v_fmac_f32_e32 v73, v74, v71
	v_fma_f32 v70, -v70, v73, v72
	v_div_fmas_f32 v70, v70, v71, v73
	v_div_fixup_f32 v70, v70, v69, 1.0
	v_mov_b32_e32 v244, v70
; __device__ __forceinline__ float frcp(float x) { return __builtin_amdgcn_rcpf(x); }
; __device__ __forceinline__ float gelu_erf(float v) {
;     const float av = fabsf(v), t = frcp(av * 0.2316418882f + 1.0f);
;     float qq = t * 0.5307027145f + (-0.7265760135f); qq = qq * t + 0.7107068705f; qq = qq * t + (-0.142248368f); qq = qq * t + 0.127414796f; qq = qq * t;
;     const float e = __builtin_amdgcn_exp2f((v * v) * (-0.72134752044f));
;     const float m = v * (qq * e);
;     return v < 0.f ? m : v - m;
; }
;     __device__ __forceinline__ void operator()(const f32x4 (&acc)[2][2][4][2], const Unit& u, int wr, int wc, int fr, int fq) const {
;     ...
;                     f32x4 v0 = acc[ai][bj][m][0] * rs, v1 = acc[ai][bj][m][1] * rs;
;                     if (isg) {
; #pragma unroll
;                         for (int j = 0; j < 4; ++j) { v0[j] = gelu_erf(v0[j]); v1[j] = gelu_erf(v1[j]); }
;                         s1 += ((v0[0] + v0[1]) + (v0[2] + v0[3])) + ((v1[0] + v1[1]) + (v1[2] + v1[3]));
;                         s2 += ((v0[0] * v0[0] + v0[1] * v0[1]) + (v0[2] * v0[2] + v0[3] * v0[3])) + ((v1[0] * v1[0] + v1[1] * v1[1]) + (v1[2] * v1[2] + v1[3] * v1[3]));
;                     }
.Lmy_z4_join:
	s_and_b64 vcc, exec, s[10:11]
	v_pk_mul_f32 v[72:73], v[64:65], v[70:71] op_sel_hi:[1,0]
	v_pk_mul_f32 v[74:75], v[62:63], v[70:71] op_sel_hi:[1,0]
	v_pk_mul_f32 v[60:61], v[60:61], v[70:71] op_sel_hi:[1,0]
	v_pk_mul_f32 v[58:59], v[58:59], v[70:71] op_sel_hi:[1,0]
	s_cbranch_vccnz .LBB0_619
	v_fma_f32 v62, |v74|, s0, 1.0
	v_rcp_f32_e32 v63, v62
	v_fma_f32 v62, |v58|, s0, 1.0
	v_rcp_f32_e32 v62, v62
	v_mul_f32_e32 v64, v74, v74
	v_mul_f32_e32 v64, 0xbf38aa3b, v64
	v_mul_f32_e32 v69, v58, v58
	v_exp_f32_e32 v65, v64
	v_fmamk_f32 v64, v62, 0x3f07dc22, v150
	v_mul_f32_e32 v69, 0xbf38aa3b, v69
	v_fmaak_f32 v64, v62, v64, 0x3f35f0e3
	v_exp_f32_e32 v69, v69
	v_fmaak_f32 v64, v62, v64, 0xbe11a98e
	v_fmaak_f32 v64, v62, v64, 0x3e027906
	v_mul_f32_e32 v62, v62, v64
	v_mul_f32_e32 v76, v69, v62
	v_fma_f32 v62, |v75|, s0, 1.0
	v_rcp_f32_e32 v62, v62
	v_mul_f32_e32 v64, v75, v75
	v_mul_f32_e32 v64, 0xbf38aa3b, v64
	v_exp_f32_e32 v64, v64
	v_pk_fma_f32 v[78:79], v[62:63], s[48:49], v[150:151] op_sel_hi:[1,0,0]
	v_fma_f32 v69, |v59|, s0, 1.0
	v_pk_fma_f32 v[78:79], v[62:63], v[78:79], s[56:57] op_sel_hi:[1,1,0]
	v_rcp_f32_e32 v69, v69
	v_pk_fma_f32 v[78:79], v[62:63], v[78:79], s[60:61] op_sel_hi:[1,1,0]
	v_fma_f32 v71, |v72|, s0, 1.0
	v_pk_fma_f32 v[78:79], v[62:63], v[78:79], s[62:63] op_sel_hi:[1,1,0]
	v_rcp_f32_e32 v71, v71
	v_pk_mul_f32 v[62:63], v[62:63], v[78:79]
	v_fma_f32 v77, |v60|, s0, 1.0
	v_pk_mul_f32 v[62:63], v[64:65], v[62:63]
	v_mul_f32_e32 v65, v59, v59
	v_fmamk_f32 v64, v69, 0x3f07dc22, v150
	v_mul_f32_e32 v65, 0xbf38aa3b, v65
	v_fmaak_f32 v64, v69, v64, 0x3f35f0e3
	v_exp_f32_e32 v65, v65
	v_fmaak_f32 v64, v69, v64, 0xbe11a98e
	v_fmaak_f32 v64, v69, v64, 0x3e027906
	v_mul_f32_e32 v64, v69, v64
	v_mul_f32_e32 v69, v72, v72
	v_mul_f32_e32 v64, v65, v64
	v_fmamk_f32 v65, v71, 0x3f07dc22, v150
	v_mul_f32_e32 v69, 0xbf38aa3b, v69
	v_fmaak_f32 v65, v71, v65, 0x3f35f0e3
	v_exp_f32_e32 v69, v69
	v_fmaak_f32 v65, v71, v65, 0xbe11a98e
	v_rcp_f32_e32 v77, v77
	v_fmaak_f32 v65, v71, v65, 0x3e027906
	v_mul_f32_e32 v65, v71, v65
	v_mul_f32_e32 v78, v69, v65
	v_mul_f32_e32 v69, v60, v60
	v_fmamk_f32 v65, v77, 0x3f07dc22, v150
	v_mul_f32_e32 v69, 0xbf38aa3b, v69
	v_fmaak_f32 v65, v77, v65, 0x3f35f0e3
	v_exp_f32_e32 v69, v69
	v_fma_f32 v71, |v73|, s0, 1.0
	v_fmaak_f32 v65, v77, v65, 0xbe11a98e
	v_rcp_f32_e32 v71, v71
	v_fmaak_f32 v65, v77, v65, 0x3e027906
	v_mul_f32_e32 v65, v77, v65
	v_mul_f32_e32 v80, v69, v65
	v_mul_f32_e32 v69, v73, v73
	v_fmamk_f32 v65, v71, 0x3f07dc22, v150
	v_mul_f32_e32 v69, 0xbf38aa3b, v69
	v_fmaak_f32 v65, v71, v65, 0x3f35f0e3
	v_exp_f32_e32 v69, v69
	v_fma_f32 v77, |v61|, s0, 1.0
	v_fmaak_f32 v65, v71, v65, 0xbe11a98e
	v_rcp_f32_e32 v77, v77
	v_fmaak_f32 v65, v71, v65, 0x3e027906
	v_mul_f32_e32 v65, v71, v65
	v_mul_f32_e32 v82, v69, v65
	v_mul_f32_e32 v69, v61, v61
	v_fmamk_f32 v65, v77, 0x3f07dc22, v150
	v_mul_f32_e32 v69, 0xbf38aa3b, v69
	v_fmaak_f32 v65, v77, v65, 0x3f35f0e3
	v_exp_f32_e32 v69, v69
	v_fmaak_f32 v65, v77, v65, 0xbe11a98e
	v_fmaak_f32 v65, v77, v65, 0x3e027906
	v_mul_f32_e32 v65, v77, v65
	v_pk_mul_f32 v[86:87], v[74:75], v[62:63] op_sel:[1,0] op_sel_hi:[0,1]
	v_mov_b32_e32 v83, v62
	v_mov_b32_e32 v79, v62
	v_pk_fma_f32 v[62:63], v[74:75], v[62:63], v[74:75] op_sel:[1,0,1] op_sel_hi:[0,1,0] neg_lo:[1,0,0] neg_hi:[1,0,0]
	v_cmp_gt_f32_e64 s[14:15], 0, v74
	v_mul_f32_e32 v84, v69, v65
	v_mov_b32_e32 v88, v73
	v_mov_b32_e32 v89, v75
	v_mov_b32_e32 v92, v72
	v_mov_b32_e32 v93, v75
	v_pk_mov_b32 v[100:101], v[58:59], v[72:73] op_sel:[1,0]
	v_mov_b32_e32 v65, v78
	v_cndmask_b32_e64 v87, v63, v87, s[14:15]
	v_cmp_gt_f32_e64 s[14:15], 0, v75
	v_pk_mul_f32 v[90:91], v[88:89], v[82:83]
	v_pk_mul_f32 v[94:95], v[92:93], v[78:79]
	v_mov_b32_e32 v96, v58
	v_mov_b32_e32 v97, v72
	v_mov_b32_e32 v77, v78
	v_pk_mul_f32 v[102:103], v[100:101], v[64:65]
	v_mov_b32_e32 v104, v60
	v_mov_b32_e32 v105, v73
	v_mov_b32_e32 v81, v82
	v_pk_fma_f32 v[78:79], v[92:93], v[78:79], v[92:93] neg_lo:[1,0,0] neg_hi:[1,0,0]
	v_mov_b32_e32 v85, v82
	v_pk_fma_f32 v[82:83], v[88:89], v[82:83], v[88:89] neg_lo:[1,0,0] neg_hi:[1,0,0]
	v_cndmask_b32_e64 v86, v62, v86, s[14:15]
	v_pk_fma_f32 v[62:63], v[100:101], v[64:65], v[100:101] neg_lo:[1,0,0] neg_hi:[1,0,0]
	v_cmp_gt_f32_e64 s[16:17], 0, v59
	v_pk_mul_f32 v[98:99], v[96:97], v[76:77]
	v_pk_mul_f32 v[106:107], v[104:105], v[80:81]
	v_pk_fma_f32 v[76:77], v[96:97], v[76:77], v[96:97] neg_lo:[1,0,0] neg_hi:[1,0,0]
	v_cmp_gt_f32_e32 vcc, 0, v72
	v_mov_b32_e32 v72, v61
	v_cmp_gt_f32_e64 s[18:19], 0, v58
	v_cndmask_b32_e64 v65, v79, v95, s[14:15]
	v_pk_fma_f32 v[74:75], v[104:105], v[80:81], v[104:105] neg_lo:[1,0,0] neg_hi:[1,0,0]
	v_cndmask_b32_e64 v79, v83, v91, s[14:15]
	v_cmp_gt_f32_e64 s[14:15], 0, v73
	v_cndmask_b32_e64 v80, v62, v102, s[16:17]
	v_mov_b32_e32 v62, v87
	v_pk_mul_f32 v[92:93], v[72:73], v[84:85]
	v_cndmask_b32_e32 v59, v77, v99, vcc
	v_cndmask_b32_e64 v58, v76, v98, s[18:19]
	v_cndmask_b32_e32 v64, v78, v94, vcc
	v_pk_fma_f32 v[76:77], v[72:73], v[84:85], v[72:73] neg_lo:[1,0,0] neg_hi:[1,0,0]
	v_cndmask_b32_e64 v78, v82, v90, s[14:15]
	v_cndmask_b32_e32 v81, v63, v103, vcc
	v_cmp_gt_f32_e32 vcc, 0, v60
	v_pk_add_f32 v[62:63], v[62:63], v[86:87] op_sel_hi:[0,1]
	v_pk_mul_f32 v[72:73], v[86:87], v[86:87]
	v_cmp_gt_f32_e64 s[18:19], 0, v61
	v_cndmask_b32_e64 v61, v75, v107, s[14:15]
	v_cndmask_b32_e32 v60, v74, v106, vcc
	v_mov_b32_e32 v63, v73
	v_pk_add_f32 v[72:73], v[64:65], v[78:79]
	v_pk_mul_f32 v[74:75], v[64:65], v[78:79]
	v_cndmask_b32_e64 v77, v77, v93, s[14:15]
	v_mov_b32_e32 v73, v75
	v_cndmask_b32_e64 v76, v76, v92, s[18:19]
	v_pk_add_f32 v[62:63], v[62:63], v[72:73]
	v_pk_add_f32 v[72:73], v[58:59], v[80:81]
	v_pk_mul_f32 v[74:75], v[58:59], v[80:81]
	v_pk_mul_f32 v[82:83], v[60:61], v[76:77]
	v_mov_b32_e32 v73, v75
	v_pk_add_f32 v[74:75], v[60:61], v[76:77]
	v_mov_b32_e32 v81, v76
	v_mov_b32_e32 v75, v83
	v_pk_add_f32 v[72:73], v[72:73], v[74:75]
	v_mov_b32_e32 v59, v60
	v_pk_add_f32 v[62:63], v[62:63], v[72:73]
	v_pk_mul_f32 v[72:73], v[80:81], v[80:81]
	v_mov_b32_e32 v74, v87
	v_pk_fma_f32 v[72:73], v[58:59], v[58:59], v[72:73]
	v_mov_b32_e32 v75, v86
	v_pk_add_f32 v[72:73], v[72:73], v[72:73] op_sel_hi:[0,1]
	v_mov_b32_e32 v139, v73
	v_pk_add_f32 v[62:63], v[62:63], v[138:139]
	v_mov_b32_e32 v72, v64
	v_mov_b32_e32 v73, v78
	v_mov_b32_e32 v59, v80
	v_mov_b32_e32 v61, v76
	s_branch .LBB0_620

; __device__ __forceinline__ float row_rstd_q(const float* ssq, int row, int fq) {
;     const f32x4 a = ((const f32x4*)(ssq + (size_t)row * 16))[fq];
;     float s = (a[0] + a[1]) + (a[2] + a[3]);
;     s += __shfl_xor(s, 16); s += __shfl_xor(s, 32);
;     return 1.0f / sqrtf(s * (1.0f / 1024.0f) + 1e-6f);
; }
;     __device__ __forceinline__ void operator()(const f32x4 (&acc)[2][2][4][2], const Unit& u, int wr, int wc, int fr, int fq) const {
;     ...
;                 const int row = row0 + ai * 128 + m * 16; const float rs = row_rstd_q(ssq, row, fq); float s1 = 0.f, s2 = 0.f;
.LBB0_626:
	s_waitcnt lgkmcnt(1)
	v_add_u32_e32 v52, 0x90, v152
	s_waitcnt lgkmcnt(0)
	v_ashrrev_i32_e32 v53, 31, v52
	v_lshlrev_b64 v[50:51], 6, v[52:53]
	s_cmp_eq_u32 s101, 0
	s_cbranch_scc1 .Lmy_z5_miss
	v_mov_b32_e32 v54, v245
	s_branch .Lmy_z5_join
.Lmy_z5_miss:
	v_lshl_add_u64 v[54:55], v[140:141], 0, v[50:51]
	global_load_dwordx4 v[54:57], v[54:55], off
	s_waitcnt vmcnt(0)
	v_mov_b32_e32 v58, v55
	v_mov_b32_e32 v59, v56
	v_mov_b32_e32 v55, v57
	v_pk_add_f32 v[54:55], v[58:59], v[54:55]
	s_nop 0
	v_add_f32_e32 v53, v54, v55
	ds_bpermute_b32 v54, v153, v53
	s_waitcnt lgkmcnt(0)
	v_add_f32_e32 v53, v53, v54
	ds_bpermute_b32 v54, v171, v53
	s_waitcnt lgkmcnt(0)
	v_add_f32_e32 v53, v53, v54
	v_fmamk_f32 v53, v53, 0x3a800000, v169
	v_mul_f32_e32 v54, 0x4f800000, v53
	v_cmp_gt_f32_e32 vcc, s21, v53
	s_nop 1
	v_cndmask_b32_e32 v53, v53, v54, vcc
	v_sqrt_f32_e32 v54, v53
	s_nop 0
	v_add_u32_e32 v55, -1, v54
	v_add_u32_e32 v56, 1, v54
	v_fma_f32 v57, -v55, v54, v53
	v_fma_f32 v58, -v56, v54, v53
	v_cmp_ge_f32_e64 s[14:15], 0, v57
	s_nop 1
	v_cndmask_b32_e64 v54, v54, v55, s[14:15]
	v_cmp_lt_f32_e64 s[14:15], 0, v58
	s_nop 1
	v_cndmask_b32_e64 v54, v54, v56, s[14:15]
	v_mul_f32_e32 v55, 0x37800000, v54
	v_cndmask_b32_e32 v54, v54, v55, vcc
	v_cmp_class_f32_e32 vcc, v53, v170
	s_nop 1
	v_cndmask_b32_e32 v53, v54, v53, vcc
	v_div_scale_f32 v54, s[14:15], v53, v53, 1.0
	v_rcp_f32_e32 v55, v54
	v_div_scale_f32 v56, vcc, 1.0, v53, 1.0
	v_fma_f32 v57, -v54, v55, 1.0
	v_fmac_f32_e32 v55, v57, v55
	v_mul_f32_e32 v57, v56, v55
	v_fma_f32 v58, -v54, v57, v56
	v_fmac_f32_e32 v57, v58, v55
	v_fma_f32 v54, -v54, v57, v56
	v_div_fmas_f32 v54, v54, v55, v57
	v_div_fixup_f32 v54, v54, v53, 1.0
	v_mov_b32_e32 v245, v54
; __device__ __forceinline__ float frcp(float x) { return __builtin_amdgcn_rcpf(x); }
; __device__ __forceinline__ float gelu_erf(float v) {
;     const float av = fabsf(v), t = frcp(av * 0.2316418882f + 1.0f);
;     float qq = t * 0.5307027145f + (-0.7265760135f); qq = qq * t + 0.7107068705f; qq = qq * t + (-0.142248368f); qq = qq * t + 0.127414796f; qq = qq * t;
;     const float e = __builtin_amdgcn_exp2f((v * v) * (-0.72134752044f));
;     const float m = v * (qq * e);
;     return v < 0.f ? m : v - m;
; }
;     __device__ __forceinline__ void operator()(const f32x4 (&acc)[2][2][4][2], const Unit& u, int wr, int wc, int fr, int fq) const {
;     ...
;                 const int row = row0 + ai * 128 + m * 16; const float rs = row_rstd_q(ssq, row, fq); float s1 = 0.f, s2 = 0.f;
; #pragma unroll
;                 for (int bj = 0; bj < 2; ++bj) {
;                     f32x4 v0 = acc[ai][bj][m][0] * rs, v1 = acc[ai][bj][m][1] * rs;
;                     if (isg) {
; #pragma unroll
;                         for (int j = 0; j < 4; ++j) { v0[j] = gelu_erf(v0[j]); v1[j] = gelu_erf(v1[j]); }
;                         s1 += ((v0[0] + v0[1]) + (v0[2] + v0[3])) + ((v1[0] + v1[1]) + (v1[2] + v1[3]));
;                         s2 += ((v0[0] * v0[0] + v0[1] * v0[1]) + (v0[2] * v0[2] + v0[3] * v0[3])) + ((v1[0] * v1[0] + v1[1] * v1[1]) + (v1[2] * v1[2] + v1[3] * v1[3]));
;                     }
.Lmy_z5_join:
	s_and_b64 vcc, exec, s[10:11]
	v_pk_mul_f32 v[56:57], v[48:49], v[54:55] op_sel_hi:[1,0]
	v_pk_mul_f32 v[58:59], v[46:47], v[54:55] op_sel_hi:[1,0]
	v_pk_mul_f32 v[44:45], v[44:45], v[54:55] op_sel_hi:[1,0]
	v_pk_mul_f32 v[42:43], v[42:43], v[54:55] op_sel_hi:[1,0]
	s_cbranch_vccnz .LBB0_628
	v_fma_f32 v46, |v58|, s0, 1.0
	v_rcp_f32_e32 v47, v46
	v_fma_f32 v46, |v42|, s0, 1.0
	v_rcp_f32_e32 v46, v46
	v_mul_f32_e32 v48, v58, v58
	v_mul_f32_e32 v48, 0xbf38aa3b, v48
	v_mul_f32_e32 v53, v42, v42
	v_exp_f32_e32 v49, v48
	v_fmamk_f32 v48, v46, 0x3f07dc22, v150
	v_mul_f32_e32 v53, 0xbf38aa3b, v53
	v_fmaak_f32 v48, v46, v48, 0x3f35f0e3
	v_exp_f32_e32 v53, v53
	v_fmaak_f32 v48, v46, v48, 0xbe11a98e
	v_fmaak_f32 v48, v46, v48, 0x3e027906
	v_mul_f32_e32 v46, v46, v48
	v_mul_f32_e32 v60, v53, v46
	v_fma_f32 v46, |v59|, s0, 1.0
	v_rcp_f32_e32 v46, v46
	v_mul_f32_e32 v48, v59, v59
	v_mul_f32_e32 v48, 0xbf38aa3b, v48
	v_exp_f32_e32 v48, v48
	v_pk_fma_f32 v[62:63], v[46:47], s[48:49], v[150:151] op_sel_hi:[1,0,0]
	v_fma_f32 v53, |v43|, s0, 1.0
	v_pk_fma_f32 v[62:63], v[46:47], v[62:63], s[56:57] op_sel_hi:[1,1,0]
	v_rcp_f32_e32 v53, v53
	v_pk_fma_f32 v[62:63], v[46:47], v[62:63], s[60:61] op_sel_hi:[1,1,0]
	v_fma_f32 v55, |v56|, s0, 1.0
	v_pk_fma_f32 v[62:63], v[46:47], v[62:63], s[62:63] op_sel_hi:[1,1,0]
	v_rcp_f32_e32 v55, v55
	v_pk_mul_f32 v[46:47], v[46:47], v[62:63]
	v_fma_f32 v61, |v44|, s0, 1.0
	v_pk_mul_f32 v[46:47], v[48:49], v[46:47]
	v_mul_f32_e32 v49, v43, v43
	v_fmamk_f32 v48, v53, 0x3f07dc22, v150
	v_mul_f32_e32 v49, 0xbf38aa3b, v49
	v_fmaak_f32 v48, v53, v48, 0x3f35f0e3
	v_exp_f32_e32 v49, v49
	v_fmaak_f32 v48, v53, v48, 0xbe11a98e
	v_fmaak_f32 v48, v53, v48, 0x3e027906
	v_mul_f32_e32 v48, v53, v48
	v_mul_f32_e32 v53, v56, v56
	v_mul_f32_e32 v48, v49, v48
	v_fmamk_f32 v49, v55, 0x3f07dc22, v150
	v_mul_f32_e32 v53, 0xbf38aa3b, v53
	v_fmaak_f32 v49, v55, v49, 0x3f35f0e3
	v_exp_f32_e32 v53, v53
	v_fmaak_f32 v49, v55, v49, 0xbe11a98e
	v_rcp_f32_e32 v61, v61
	v_fmaak_f32 v49, v55, v49, 0x3e027906
	v_mul_f32_e32 v49, v55, v49
	v_mul_f32_e32 v62, v53, v49
	v_mul_f32_e32 v53, v44, v44
	v_fmamk_f32 v49, v61, 0x3f07dc22, v150
	v_mul_f32_e32 v53, 0xbf38aa3b, v53
	v_fmaak_f32 v49, v61, v49, 0x3f35f0e3
	v_exp_f32_e32 v53, v53
	v_fma_f32 v55, |v57|, s0, 1.0
	v_fmaak_f32 v49, v61, v49, 0xbe11a98e
	v_rcp_f32_e32 v55, v55
	v_fmaak_f32 v49, v61, v49, 0x3e027906
	v_mul_f32_e32 v49, v61, v49
	v_mul_f32_e32 v64, v53, v49
	v_mul_f32_e32 v53, v57, v57
	v_fmamk_f32 v49, v55, 0x3f07dc22, v150
	v_mul_f32_e32 v53, 0xbf38aa3b, v53
	v_fmaak_f32 v49, v55, v49, 0x3f35f0e3
	v_exp_f32_e32 v53, v53
	v_fma_f32 v61, |v45|, s0, 1.0
	v_fmaak_f32 v49, v55, v49, 0xbe11a98e
	v_rcp_f32_e32 v61, v61
	v_fmaak_f32 v49, v55, v49, 0x3e027906
	v_mul_f32_e32 v49, v55, v49
	v_mul_f32_e32 v66, v53, v49
	v_mul_f32_e32 v53, v45, v45
	v_fmamk_f32 v49, v61, 0x3f07dc22, v150
	v_mul_f32_e32 v53, 0xbf38aa3b, v53
	v_fmaak_f32 v49, v61, v49, 0x3f35f0e3
	v_exp_f32_e32 v53, v53
	v_fmaak_f32 v49, v61, v49, 0xbe11a98e
	v_fmaak_f32 v49, v61, v49, 0x3e027906
	v_mul_f32_e32 v49, v61, v49
	v_pk_mul_f32 v[70:71], v[58:59], v[46:47] op_sel:[1,0] op_sel_hi:[0,1]
	v_mov_b32_e32 v67, v46
	v_mov_b32_e32 v63, v46
	v_pk_fma_f32 v[46:47], v[58:59], v[46:47], v[58:59] op_sel:[1,0,1] op_sel_hi:[0,1,0] neg_lo:[1,0,0] neg_hi:[1,0,0]
	v_cmp_gt_f32_e64 s[14:15], 0, v58
	v_mul_f32_e32 v68, v53, v49
	v_mov_b32_e32 v72, v57
	v_mov_b32_e32 v73, v59
	v_mov_b32_e32 v76, v56
	v_mov_b32_e32 v77, v59
	v_pk_mov_b32 v[84:85], v[42:43], v[56:57] op_sel:[1,0]
	v_mov_b32_e32 v49, v62
	v_cndmask_b32_e64 v71, v47, v71, s[14:15]
	v_cmp_gt_f32_e64 s[14:15], 0, v59
	v_pk_mul_f32 v[74:75], v[72:73], v[66:67]
	v_pk_mul_f32 v[78:79], v[76:77], v[62:63]
	v_mov_b32_e32 v80, v42
	v_mov_b32_e32 v81, v56
	v_mov_b32_e32 v61, v62
	v_pk_mul_f32 v[86:87], v[84:85], v[48:49]
	v_mov_b32_e32 v88, v44
	v_mov_b32_e32 v89, v57
	v_mov_b32_e32 v65, v66
	v_pk_fma_f32 v[62:63], v[76:77], v[62:63], v[76:77] neg_lo:[1,0,0] neg_hi:[1,0,0]
	v_mov_b32_e32 v69, v66
	v_pk_fma_f32 v[66:67], v[72:73], v[66:67], v[72:73] neg_lo:[1,0,0] neg_hi:[1,0,0]
	v_cndmask_b32_e64 v70, v46, v70, s[14:15]
	v_pk_fma_f32 v[46:47], v[84:85], v[48:49], v[84:85] neg_lo:[1,0,0] neg_hi:[1,0,0]
	v_cmp_gt_f32_e64 s[16:17], 0, v43
	v_pk_mul_f32 v[82:83], v[80:81], v[60:61]
	v_pk_mul_f32 v[90:91], v[88:89], v[64:65]
	v_pk_fma_f32 v[60:61], v[80:81], v[60:61], v[80:81] neg_lo:[1,0,0] neg_hi:[1,0,0]
	v_cmp_gt_f32_e32 vcc, 0, v56
	v_mov_b32_e32 v56, v45
	v_cmp_gt_f32_e64 s[18:19], 0, v42
	v_cndmask_b32_e64 v49, v63, v79, s[14:15]
	v_pk_fma_f32 v[58:59], v[88:89], v[64:65], v[88:89] neg_lo:[1,0,0] neg_hi:[1,0,0]
	v_cndmask_b32_e64 v63, v67, v75, s[14:15]
	v_cmp_gt_f32_e64 s[14:15], 0, v57
	v_cndmask_b32_e64 v64, v46, v86, s[16:17]
	v_mov_b32_e32 v46, v71
	v_pk_mul_f32 v[76:77], v[56:57], v[68:69]
	v_cndmask_b32_e32 v43, v61, v83, vcc
	v_cndmask_b32_e64 v42, v60, v82, s[18:19]
	v_cndmask_b32_e32 v48, v62, v78, vcc
	v_pk_fma_f32 v[60:61], v[56:57], v[68:69], v[56:57] neg_lo:[1,0,0] neg_hi:[1,0,0]
	v_cndmask_b32_e64 v62, v66, v74, s[14:15]
	v_cndmask_b32_e32 v65, v47, v87, vcc
	v_cmp_gt_f32_e32 vcc, 0, v44
	v_pk_add_f32 v[46:47], v[46:47], v[70:71] op_sel_hi:[0,1]
	v_pk_mul_f32 v[56:57], v[70:71], v[70:71]
	v_cmp_gt_f32_e64 s[18:19], 0, v45
	v_cndmask_b32_e64 v45, v59, v91, s[14:15]
	v_cndmask_b32_e32 v44, v58, v90, vcc
	v_mov_b32_e32 v47, v57
	v_pk_add_f32 v[56:57], v[48:49], v[62:63]
	v_pk_mul_f32 v[58:59], v[48:49], v[62:63]
	v_cndmask_b32_e64 v61, v61, v77, s[14:15]
	v_mov_b32_e32 v57, v59
	v_cndmask_b32_e64 v60, v60, v76, s[18:19]
	v_pk_add_f32 v[46:47], v[46:47], v[56:57]
	v_pk_add_f32 v[56:57], v[42:43], v[64:65]
	v_pk_mul_f32 v[58:59], v[42:43], v[64:65]
	v_pk_mul_f32 v[66:67], v[44:45], v[60:61]
	v_mov_b32_e32 v57, v59
	v_pk_add_f32 v[58:59], v[44:45], v[60:61]
	v_mov_b32_e32 v65, v60
	v_mov_b32_e32 v59, v67
	v_pk_add_f32 v[56:57], v[56:57], v[58:59]
	v_mov_b32_e32 v43, v44
	v_pk_add_f32 v[46:47], v[46:47], v[56:57]
	v_pk_mul_f32 v[56:57], v[64:65], v[64:65]
	v_mov_b32_e32 v58, v71
	v_pk_fma_f32 v[56:57], v[42:43], v[42:43], v[56:57]
	v_mov_b32_e32 v59, v70
	v_pk_add_f32 v[56:57], v[56:57], v[56:57] op_sel_hi:[0,1]
	v_mov_b32_e32 v139, v57
	v_pk_add_f32 v[46:47], v[46:47], v[138:139]
	v_mov_b32_e32 v56, v48
	v_mov_b32_e32 v57, v62
	v_mov_b32_e32 v43, v64
	v_mov_b32_e32 v45, v60
	s_branch .LBB0_629

; __device__ __forceinline__ float row_rstd_q(const float* ssq, int row, int fq) {
;     const f32x4 a = ((const f32x4*)(ssq + (size_t)row * 16))[fq];
;     float s = (a[0] + a[1]) + (a[2] + a[3]);
;     s += __shfl_xor(s, 16); s += __shfl_xor(s, 32);
;     return 1.0f / sqrtf(s * (1.0f / 1024.0f) + 1e-6f);
; }
.LBB0_635:
	s_waitcnt lgkmcnt(1)
	v_add_u32_e32 v36, 0xa0, v152
	s_waitcnt lgkmcnt(0)
	v_ashrrev_i32_e32 v37, 31, v36
	v_lshlrev_b64 v[34:35], 6, v[36:37]
	s_cmp_eq_u32 s101, 0
	s_cbranch_scc1 .Lmy_z6_miss
	v_mov_b32_e32 v38, v246
	s_branch .Lmy_z6_join
.Lmy_z6_miss:
	v_lshl_add_u64 v[38:39], v[140:141], 0, v[34:35]
	global_load_dwordx4 v[38:41], v[38:39], off
	s_waitcnt vmcnt(0)
	v_mov_b32_e32 v42, v39
	v_mov_b32_e32 v43, v40
	v_mov_b32_e32 v39, v41
	v_pk_add_f32 v[38:39], v[42:43], v[38:39]
	s_nop 0
	v_add_f32_e32 v37, v38, v39
	ds_bpermute_b32 v38, v153, v37
	s_waitcnt lgkmcnt(0)
	v_add_f32_e32 v37, v37, v38
	ds_bpermute_b32 v38, v171, v37
	s_waitcnt lgkmcnt(0)
	v_add_f32_e32 v37, v37, v38
	v_fmamk_f32 v37, v37, 0x3a800000, v169
	v_mul_f32_e32 v38, 0x4f800000, v37
	v_cmp_gt_f32_e32 vcc, s21, v37
	s_nop 1
	v_cndmask_b32_e32 v37, v37, v38, vcc
	v_sqrt_f32_e32 v38, v37
	s_nop 0
	v_add_u32_e32 v39, -1, v38
	v_add_u32_e32 v40, 1, v38
	v_fma_f32 v41, -v39, v38, v37
	v_fma_f32 v42, -v40, v38, v37
	v_cmp_ge_f32_e64 s[14:15], 0, v41
	s_nop 1
	v_cndmask_b32_e64 v38, v38, v39, s[14:15]
	v_cmp_lt_f32_e64 s[14:15], 0, v42
	s_nop 1
	v_cndmask_b32_e64 v38, v38, v40, s[14:15]
	v_mul_f32_e32 v39, 0x37800000, v38
	v_cndmask_b32_e32 v38, v38, v39, vcc
	v_cmp_class_f32_e32 vcc, v37, v170
	s_nop 1
	v_cndmask_b32_e32 v37, v38, v37, vcc
	v_div_scale_f32 v38, s[14:15], v37, v37, 1.0
	v_rcp_f32_e32 v39, v38
	v_div_scale_f32 v40, vcc, 1.0, v37, 1.0
	v_fma_f32 v41, -v38, v39, 1.0
	v_fmac_f32_e32 v39, v41, v39
	v_mul_f32_e32 v41, v40, v39
	v_fma_f32 v42, -v38, v41, v40
	v_fmac_f32_e32 v41, v42, v39
	v_fma_f32 v38, -v38, v41, v40
	v_div_fmas_f32 v38, v38, v39, v41
	v_div_fixup_f32 v38, v38, v37, 1.0
	v_mov_b32_e32 v246, v38
; __device__ __forceinline__ float frcp(float x) { return __builtin_amdgcn_rcpf(x); }
; __device__ __forceinline__ float gelu_erf(float v) {
;     const float av = fabsf(v), t = frcp(av * 0.2316418882f + 1.0f);
;     float qq = t * 0.5307027145f + (-0.7265760135f); qq = qq * t + 0.7107068705f; qq = qq * t + (-0.142248368f); qq = qq * t + 0.127414796f; qq = qq * t;
;     const float e = __builtin_amdgcn_exp2f((v * v) * (-0.72134752044f));
;     const float m = v * (qq * e);
;     return v < 0.f ? m : v - m;
; }
;     __device__ __forceinline__ void operator()(const f32x4 (&acc)[2][2][4][2], const Unit& u, int wr, int wc, int fr, int fq) const {
;     ...
;                 const int row = row0 + ai * 128 + m * 16; const float rs = row_rstd_q(ssq, row, fq); float s1 = 0.f, s2 = 0.f;
; #pragma unroll
;                 for (int bj = 0; bj < 2; ++bj) {
;                     f32x4 v0 = acc[ai][bj][m][0] * rs, v1 = acc[ai][bj][m][1] * rs;
;                     if (isg) {
; #pragma unroll
;                         for (int j = 0; j < 4; ++j) { v0[j] = gelu_erf(v0[j]); v1[j] = gelu_erf(v1[j]); }
;                         s1 += ((v0[0] + v0[1]) + (v0[2] + v0[3])) + ((v1[0] + v1[1]) + (v1[2] + v1[3]));
;                         s2 += ((v0[0] * v0[0] + v0[1] * v0[1]) + (v0[2] * v0[2] + v0[3] * v0[3])) + ((v1[0] * v1[0] + v1[1] * v1[1]) + (v1[2] * v1[2] + v1[3] * v1[3]));
;                     }
.Lmy_z6_join:
	s_and_b64 vcc, exec, s[10:11]
	v_pk_mul_f32 v[40:41], v[32:33], v[38:39] op_sel_hi:[1,0]
	v_pk_mul_f32 v[42:43], v[30:31], v[38:39] op_sel_hi:[1,0]
	v_pk_mul_f32 v[28:29], v[28:29], v[38:39] op_sel_hi:[1,0]
	v_pk_mul_f32 v[26:27], v[26:27], v[38:39] op_sel_hi:[1,0]
	s_cbranch_vccnz .LBB0_637
	v_fma_f32 v30, |v42|, s0, 1.0
	v_rcp_f32_e32 v31, v30
	v_fma_f32 v30, |v26|, s0, 1.0
	v_rcp_f32_e32 v30, v30
	v_mul_f32_e32 v32, v42, v42
	v_mul_f32_e32 v32, 0xbf38aa3b, v32
	v_mul_f32_e32 v37, v26, v26
	v_exp_f32_e32 v33, v32
	v_fmamk_f32 v32, v30, 0x3f07dc22, v150
	v_mul_f32_e32 v37, 0xbf38aa3b, v37
	v_fmaak_f32 v32, v30, v32, 0x3f35f0e3
	v_exp_f32_e32 v37, v37
	v_fmaak_f32 v32, v30, v32, 0xbe11a98e
	v_fmaak_f32 v32, v30, v32, 0x3e027906
	v_mul_f32_e32 v30, v30, v32
	v_mul_f32_e32 v44, v37, v30
	v_fma_f32 v30, |v43|, s0, 1.0
	v_rcp_f32_e32 v30, v30
	v_mul_f32_e32 v32, v43, v43
	v_mul_f32_e32 v32, 0xbf38aa3b, v32
	v_exp_f32_e32 v32, v32
	v_pk_fma_f32 v[46:47], v[30:31], s[48:49], v[150:151] op_sel_hi:[1,0,0]
	v_fma_f32 v37, |v27|, s0, 1.0
	v_pk_fma_f32 v[46:47], v[30:31], v[46:47], s[56:57] op_sel_hi:[1,1,0]
	v_rcp_f32_e32 v37, v37
	v_pk_fma_f32 v[46:47], v[30:31], v[46:47], s[60:61] op_sel_hi:[1,1,0]
	v_fma_f32 v39, |v40|, s0, 1.0
	v_pk_fma_f32 v[46:47], v[30:31], v[46:47], s[62:63] op_sel_hi:[1,1,0]
	v_rcp_f32_e32 v39, v39
	v_pk_mul_f32 v[30:31], v[30:31], v[46:47]
	v_fma_f32 v45, |v28|, s0, 1.0
	v_pk_mul_f32 v[30:31], v[32:33], v[30:31]
	v_mul_f32_e32 v33, v27, v27
	v_fmamk_f32 v32, v37, 0x3f07dc22, v150
	v_mul_f32_e32 v33, 0xbf38aa3b, v33
	v_fmaak_f32 v32, v37, v32, 0x3f35f0e3
	v_exp_f32_e32 v33, v33
	v_fmaak_f32 v32, v37, v32, 0xbe11a98e
	v_fmaak_f32 v32, v37, v32, 0x3e027906
	v_mul_f32_e32 v32, v37, v32
	v_mul_f32_e32 v37, v40, v40
	v_mul_f32_e32 v32, v33, v32
	v_fmamk_f32 v33, v39, 0x3f07dc22, v150
	v_mul_f32_e32 v37, 0xbf38aa3b, v37
	v_fmaak_f32 v33, v39, v33, 0x3f35f0e3
	v_exp_f32_e32 v37, v37
	v_fmaak_f32 v33, v39, v33, 0xbe11a98e
	v_rcp_f32_e32 v45, v45
	v_fmaak_f32 v33, v39, v33, 0x3e027906
	v_mul_f32_e32 v33, v39, v33
	v_mul_f32_e32 v46, v37, v33
	v_mul_f32_e32 v37, v28, v28
	v_fmamk_f32 v33, v45, 0x3f07dc22, v150
	v_mul_f32_e32 v37, 0xbf38aa3b, v37
	v_fmaak_f32 v33, v45, v33, 0x3f35f0e3
	v_exp_f32_e32 v37, v37
	v_fma_f32 v39, |v41|, s0, 1.0
	v_fmaak_f32 v33, v45, v33, 0xbe11a98e
	v_rcp_f32_e32 v39, v39
	v_fmaak_f32 v33, v45, v33, 0x3e027906
	v_mul_f32_e32 v33, v45, v33
	v_mul_f32_e32 v48, v37, v33
	v_mul_f32_e32 v37, v41, v41
	v_fmamk_f32 v33, v39, 0x3f07dc22, v150
	v_mul_f32_e32 v37, 0xbf38aa3b, v37
	v_fmaak_f32 v33, v39, v33, 0x3f35f0e3
	v_exp_f32_e32 v37, v37
	v_fma_f32 v45, |v29|, s0, 1.0
	v_fmaak_f32 v33, v39, v33, 0xbe11a98e
	v_rcp_f32_e32 v45, v45
	v_fmaak_f32 v33, v39, v33, 0x3e027906
	v_mul_f32_e32 v33, v39, v33
	v_mul_f32_e32 v50, v37, v33
	v_mul_f32_e32 v37, v29, v29
	v_fmamk_f32 v33, v45, 0x3f07dc22, v150
	v_mul_f32_e32 v37, 0xbf38aa3b, v37
	v_fmaak_f32 v33, v45, v33, 0x3f35f0e3
	v_exp_f32_e32 v37, v37
	v_fmaak_f32 v33, v45, v33, 0xbe11a98e
	v_fmaak_f32 v33, v45, v33, 0x3e027906
	v_mul_f32_e32 v33, v45, v33
	v_pk_mul_f32 v[54:55], v[42:43], v[30:31] op_sel:[1,0] op_sel_hi:[0,1]
	v_mov_b32_e32 v51, v30
	v_mov_b32_e32 v47, v30
	v_pk_fma_f32 v[30:31], v[42:43], v[30:31], v[42:43] op_sel:[1,0,1] op_sel_hi:[0,1,0] neg_lo:[1,0,0] neg_hi:[1,0,0]
	v_cmp_gt_f32_e64 s[14:15], 0, v42
	v_mul_f32_e32 v52, v37, v33
	v_mov_b32_e32 v56, v41
	v_mov_b32_e32 v57, v43
	v_mov_b32_e32 v60, v40
	v_mov_b32_e32 v61, v43
	v_pk_mov_b32 v[68:69], v[26:27], v[40:41] op_sel:[1,0]
	v_mov_b32_e32 v33, v46
	v_cndmask_b32_e64 v55, v31, v55, s[14:15]
	v_cmp_gt_f32_e64 s[14:15], 0, v43
	v_pk_mul_f32 v[58:59], v[56:57], v[50:51]
	v_pk_mul_f32 v[62:63], v[60:61], v[46:47]
	v_mov_b32_e32 v64, v26
	v_mov_b32_e32 v65, v40
	v_mov_b32_e32 v45, v46
	v_pk_mul_f32 v[70:71], v[68:69], v[32:33]
	v_mov_b32_e32 v72, v28
	v_mov_b32_e32 v73, v41
	v_mov_b32_e32 v49, v50
	v_pk_fma_f32 v[46:47], v[60:61], v[46:47], v[60:61] neg_lo:[1,0,0] neg_hi:[1,0,0]
	v_mov_b32_e32 v53, v50
	v_pk_fma_f32 v[50:51], v[56:57], v[50:51], v[56:57] neg_lo:[1,0,0] neg_hi:[1,0,0]
	v_cndmask_b32_e64 v54, v30, v54, s[14:15]
	v_pk_fma_f32 v[30:31], v[68:69], v[32:33], v[68:69] neg_lo:[1,0,0] neg_hi:[1,0,0]
	v_cmp_gt_f32_e64 s[16:17], 0, v27
	v_pk_mul_f32 v[66:67], v[64:65], v[44:45]
	v_pk_mul_f32 v[74:75], v[72:73], v[48:49]
	v_pk_fma_f32 v[44:45], v[64:65], v[44:45], v[64:65] neg_lo:[1,0,0] neg_hi:[1,0,0]
	v_cmp_gt_f32_e32 vcc, 0, v40
	v_mov_b32_e32 v40, v29
	v_cmp_gt_f32_e64 s[18:19], 0, v26
	v_cndmask_b32_e64 v33, v47, v63, s[14:15]
	v_pk_fma_f32 v[42:43], v[72:73], v[48:49], v[72:73] neg_lo:[1,0,0] neg_hi:[1,0,0]
	v_cndmask_b32_e64 v47, v51, v59, s[14:15]
	v_cmp_gt_f32_e64 s[14:15], 0, v41
	v_cndmask_b32_e64 v48, v30, v70, s[16:17]
	v_mov_b32_e32 v30, v55
	v_pk_mul_f32 v[60:61], v[40:41], v[52:53]
	v_cndmask_b32_e32 v27, v45, v67, vcc
	v_cndmask_b32_e64 v26, v44, v66, s[18:19]
	v_cndmask_b32_e32 v32, v46, v62, vcc
	v_pk_fma_f32 v[44:45], v[40:41], v[52:53], v[40:41] neg_lo:[1,0,0] neg_hi:[1,0,0]
	v_cndmask_b32_e64 v46, v50, v58, s[14:15]
	v_cndmask_b32_e32 v49, v31, v71, vcc
	v_cmp_gt_f32_e32 vcc, 0, v28
	v_pk_add_f32 v[30:31], v[30:31], v[54:55] op_sel_hi:[0,1]
	v_pk_mul_f32 v[40:41], v[54:55], v[54:55]
	v_cmp_gt_f32_e64 s[18:19], 0, v29
	v_cndmask_b32_e64 v29, v43, v75, s[14:15]
	v_cndmask_b32_e32 v28, v42, v74, vcc
	v_mov_b32_e32 v31, v41
	v_pk_add_f32 v[40:41], v[32:33], v[46:47]
	v_pk_mul_f32 v[42:43], v[32:33], v[46:47]
	v_cndmask_b32_e64 v45, v45, v61, s[14:15]
	v_mov_b32_e32 v41, v43
	v_cndmask_b32_e64 v44, v44, v60, s[18:19]
	v_pk_add_f32 v[30:31], v[30:31], v[40:41]
	v_pk_add_f32 v[40:41], v[26:27], v[48:49]
	v_pk_mul_f32 v[42:43], v[26:27], v[48:49]
	v_pk_mul_f32 v[50:51], v[28:29], v[44:45]
	v_mov_b32_e32 v41, v43
	v_pk_add_f32 v[42:43], v[28:29], v[44:45]
	v_mov_b32_e32 v49, v44
	v_mov_b32_e32 v43, v51
	v_pk_add_f32 v[40:41], v[40:41], v[42:43]
	v_mov_b32_e32 v27, v28
	v_pk_add_f32 v[30:31], v[30:31], v[40:41]
	v_pk_mul_f32 v[40:41], v[48:49], v[48:49]
	v_mov_b32_e32 v42, v55
	v_pk_fma_f32 v[40:41], v[26:27], v[26:27], v[40:41]
	v_mov_b32_e32 v43, v54
	v_pk_add_f32 v[40:41], v[40:41], v[40:41] op_sel_hi:[0,1]
	v_mov_b32_e32 v139, v41
	v_pk_add_f32 v[30:31], v[30:31], v[138:139]
	v_mov_b32_e32 v40, v32
	v_mov_b32_e32 v41, v46
	v_mov_b32_e32 v27, v48
	v_mov_b32_e32 v29, v44
	s_branch .LBB0_638

; __device__ __forceinline__ float row_rstd_q(const float* ssq, int row, int fq) {
;     const f32x4 a = ((const f32x4*)(ssq + (size_t)row * 16))[fq];
;     float s = (a[0] + a[1]) + (a[2] + a[3]);
;     s += __shfl_xor(s, 16); s += __shfl_xor(s, 32);
;     return 1.0f / sqrtf(s * (1.0f / 1024.0f) + 1e-6f);
; }
.LBB0_644:
	s_waitcnt lgkmcnt(1)
	v_add_u32_e32 v20, 0xb0, v152
	s_waitcnt lgkmcnt(0)
	v_ashrrev_i32_e32 v21, 31, v20
	v_lshlrev_b64 v[18:19], 6, v[20:21]
	s_cmp_eq_u32 s101, 0
	s_cbranch_scc1 .Lmy_z7_miss
	v_mov_b32_e32 v22, v247
	s_branch .Lmy_z7_join
.Lmy_z7_miss:
	v_lshl_add_u64 v[22:23], v[140:141], 0, v[18:19]
	global_load_dwordx4 v[22:25], v[22:23], off
	s_waitcnt vmcnt(0)
	v_mov_b32_e32 v26, v23
	v_mov_b32_e32 v27, v24
	v_mov_b32_e32 v23, v25
	v_pk_add_f32 v[22:23], v[26:27], v[22:23]
	s_nop 0
	v_add_f32_e32 v21, v22, v23
	ds_bpermute_b32 v22, v153, v21
	s_waitcnt lgkmcnt(0)
	v_add_f32_e32 v21, v21, v22
	ds_bpermute_b32 v22, v171, v21
	s_waitcnt lgkmcnt(0)
	v_add_f32_e32 v21, v21, v22
	v_fmamk_f32 v21, v21, 0x3a800000, v169
	v_mul_f32_e32 v22, 0x4f800000, v21
	v_cmp_gt_f32_e32 vcc, s21, v21
	s_nop 1
	v_cndmask_b32_e32 v21, v21, v22, vcc
	v_sqrt_f32_e32 v22, v21
	s_nop 0
	v_add_u32_e32 v23, -1, v22
	v_add_u32_e32 v24, 1, v22
	v_fma_f32 v25, -v23, v22, v21
	v_fma_f32 v26, -v24, v22, v21
	v_cmp_ge_f32_e64 s[14:15], 0, v25
	s_nop 1
	v_cndmask_b32_e64 v22, v22, v23, s[14:15]
	v_cmp_lt_f32_e64 s[14:15], 0, v26
	s_nop 1
	v_cndmask_b32_e64 v22, v22, v24, s[14:15]
	v_mul_f32_e32 v23, 0x37800000, v22
	v_cndmask_b32_e32 v22, v22, v23, vcc
	v_cmp_class_f32_e32 vcc, v21, v170
	s_nop 1
	v_cndmask_b32_e32 v21, v22, v21, vcc
	v_div_scale_f32 v22, s[14:15], v21, v21, 1.0
	v_rcp_f32_e32 v23, v22
	v_div_scale_f32 v24, vcc, 1.0, v21, 1.0
	v_fma_f32 v25, -v22, v23, 1.0
	v_fmac_f32_e32 v23, v25, v23
	v_mul_f32_e32 v25, v24, v23
	v_fma_f32 v26, -v22, v25, v24
	v_fmac_f32_e32 v25, v26, v23
	v_fma_f32 v22, -v22, v25, v24
	v_div_fmas_f32 v22, v22, v23, v25
	v_div_fixup_f32 v22, v22, v21, 1.0
	v_mov_b32_e32 v247, v22
; __device__ __forceinline__ float frcp(float x) { return __builtin_amdgcn_rcpf(x); }
; __device__ __forceinline__ float gelu_erf(float v) {
;     const float av = fabsf(v), t = frcp(av * 0.2316418882f + 1.0f);
;     float qq = t * 0.5307027145f + (-0.7265760135f); qq = qq * t + 0.7107068705f; qq = qq * t + (-0.142248368f); qq = qq * t + 0.127414796f; qq = qq * t;
;     const float e = __builtin_amdgcn_exp2f((v * v) * (-0.72134752044f));
;     const float m = v * (qq * e);
;     return v < 0.f ? m : v - m;
; }
;     __device__ __forceinline__ void operator()(const f32x4 (&acc)[2][2][4][2], const Unit& u, int wr, int wc, int fr, int fq) const {
;     ...
;                 const int row = row0 + ai * 128 + m * 16; const float rs = row_rstd_q(ssq, row, fq); float s1 = 0.f, s2 = 0.f;
; #pragma unroll
;                 for (int bj = 0; bj < 2; ++bj) {
;                     f32x4 v0 = acc[ai][bj][m][0] * rs, v1 = acc[ai][bj][m][1] * rs;
;                     if (isg) {
; #pragma unroll
;                         for (int j = 0; j < 4; ++j) { v0[j] = gelu_erf(v0[j]); v1[j] = gelu_erf(v1[j]); }
;                         s1 += ((v0[0] + v0[1]) + (v0[2] + v0[3])) + ((v1[0] + v1[1]) + (v1[2] + v1[3]));
;                         s2 += ((v0[0] * v0[0] + v0[1] * v0[1]) + (v0[2] * v0[2] + v0[3] * v0[3])) + ((v1[0] * v1[0] + v1[1] * v1[1]) + (v1[2] * v1[2] + v1[3] * v1[3]));
;                     }
.Lmy_z7_join:
	s_and_b64 vcc, exec, s[10:11]
	v_pk_mul_f32 v[24:25], v[16:17], v[22:23] op_sel_hi:[1,0]
	v_pk_mul_f32 v[26:27], v[14:15], v[22:23] op_sel_hi:[1,0]
	v_pk_mul_f32 v[12:13], v[12:13], v[22:23] op_sel_hi:[1,0]
	v_pk_mul_f32 v[10:11], v[10:11], v[22:23] op_sel_hi:[1,0]
	s_cbranch_vccnz .LBB0_646
	v_fma_f32 v14, |v26|, s0, 1.0
	v_rcp_f32_e32 v15, v14
	v_fma_f32 v14, |v10|, s0, 1.0
	v_rcp_f32_e32 v14, v14
	v_mul_f32_e32 v16, v26, v26
	v_mul_f32_e32 v16, 0xbf38aa3b, v16
	v_mul_f32_e32 v21, v10, v10
	v_exp_f32_e32 v17, v16
	v_fmamk_f32 v16, v14, 0x3f07dc22, v150
	v_mul_f32_e32 v21, 0xbf38aa3b, v21
	v_fmaak_f32 v16, v14, v16, 0x3f35f0e3
	v_exp_f32_e32 v21, v21
	v_fmaak_f32 v16, v14, v16, 0xbe11a98e
	v_fmaak_f32 v16, v14, v16, 0x3e027906
	v_mul_f32_e32 v14, v14, v16
	v_mul_f32_e32 v28, v21, v14
	v_fma_f32 v14, |v27|, s0, 1.0
	v_rcp_f32_e32 v14, v14
	v_mul_f32_e32 v16, v27, v27
	v_mul_f32_e32 v16, 0xbf38aa3b, v16
	v_exp_f32_e32 v16, v16
	v_pk_fma_f32 v[30:31], v[14:15], s[48:49], v[150:151] op_sel_hi:[1,0,0]
	v_fma_f32 v21, |v11|, s0, 1.0
	v_pk_fma_f32 v[30:31], v[14:15], v[30:31], s[56:57] op_sel_hi:[1,1,0]
	v_rcp_f32_e32 v21, v21
	v_pk_fma_f32 v[30:31], v[14:15], v[30:31], s[60:61] op_sel_hi:[1,1,0]
	v_fma_f32 v23, |v24|, s0, 1.0
	v_pk_fma_f32 v[30:31], v[14:15], v[30:31], s[62:63] op_sel_hi:[1,1,0]
	v_rcp_f32_e32 v23, v23
	v_pk_mul_f32 v[14:15], v[14:15], v[30:31]
	v_fma_f32 v29, |v12|, s0, 1.0
	v_pk_mul_f32 v[14:15], v[16:17], v[14:15]
	v_mul_f32_e32 v17, v11, v11
	v_fmamk_f32 v16, v21, 0x3f07dc22, v150
	v_mul_f32_e32 v17, 0xbf38aa3b, v17
	v_fmaak_f32 v16, v21, v16, 0x3f35f0e3
	v_exp_f32_e32 v17, v17
	v_fmaak_f32 v16, v21, v16, 0xbe11a98e
	v_fmaak_f32 v16, v21, v16, 0x3e027906
	v_mul_f32_e32 v16, v21, v16
	v_mul_f32_e32 v21, v24, v24
	v_mul_f32_e32 v16, v17, v16
	v_fmamk_f32 v17, v23, 0x3f07dc22, v150
	v_mul_f32_e32 v21, 0xbf38aa3b, v21
	v_fmaak_f32 v17, v23, v17, 0x3f35f0e3
	v_exp_f32_e32 v21, v21
	v_fmaak_f32 v17, v23, v17, 0xbe11a98e
	v_rcp_f32_e32 v29, v29
	v_fmaak_f32 v17, v23, v17, 0x3e027906
	v_mul_f32_e32 v17, v23, v17
	v_mul_f32_e32 v30, v21, v17
	v_mul_f32_e32 v21, v12, v12
	v_fmamk_f32 v17, v29, 0x3f07dc22, v150
	v_mul_f32_e32 v21, 0xbf38aa3b, v21
	v_fmaak_f32 v17, v29, v17, 0x3f35f0e3
	v_exp_f32_e32 v21, v21
	v_fma_f32 v23, |v25|, s0, 1.0
	v_fmaak_f32 v17, v29, v17, 0xbe11a98e
	v_rcp_f32_e32 v23, v23
	v_fmaak_f32 v17, v29, v17, 0x3e027906
	v_mul_f32_e32 v17, v29, v17
	v_mul_f32_e32 v32, v21, v17
	v_mul_f32_e32 v21, v25, v25
	v_fmamk_f32 v17, v23, 0x3f07dc22, v150
	v_mul_f32_e32 v21, 0xbf38aa3b, v21
	v_fmaak_f32 v17, v23, v17, 0x3f35f0e3
	v_exp_f32_e32 v21, v21
	v_fma_f32 v29, |v13|, s0, 1.0
	v_fmaak_f32 v17, v23, v17, 0xbe11a98e
	v_rcp_f32_e32 v29, v29
	v_fmaak_f32 v17, v23, v17, 0x3e027906
	v_mul_f32_e32 v17, v23, v17
	v_mul_f32_e32 v34, v21, v17
	v_mul_f32_e32 v21, v13, v13
	v_fmamk_f32 v17, v29, 0x3f07dc22, v150
	v_mul_f32_e32 v21, 0xbf38aa3b, v21
	v_fmaak_f32 v17, v29, v17, 0x3f35f0e3
	v_exp_f32_e32 v21, v21
	v_fmaak_f32 v17, v29, v17, 0xbe11a98e
	v_fmaak_f32 v17, v29, v17, 0x3e027906
	v_mul_f32_e32 v17, v29, v17
	v_pk_mul_f32 v[38:39], v[26:27], v[14:15] op_sel:[1,0] op_sel_hi:[0,1]
	v_mov_b32_e32 v35, v14
	v_mov_b32_e32 v31, v14
	v_pk_fma_f32 v[14:15], v[26:27], v[14:15], v[26:27] op_sel:[1,0,1] op_sel_hi:[0,1,0] neg_lo:[1,0,0] neg_hi:[1,0,0]
	v_cmp_gt_f32_e64 s[14:15], 0, v26
	v_mul_f32_e32 v36, v21, v17
	v_mov_b32_e32 v40, v25
	v_mov_b32_e32 v41, v27
	v_mov_b32_e32 v44, v24
	v_mov_b32_e32 v45, v27
	v_pk_mov_b32 v[52:53], v[10:11], v[24:25] op_sel:[1,0]
	v_mov_b32_e32 v17, v30
	v_cndmask_b32_e64 v39, v15, v39, s[14:15]
	v_cmp_gt_f32_e64 s[14:15], 0, v27
	v_pk_mul_f32 v[42:43], v[40:41], v[34:35]
	v_pk_mul_f32 v[46:47], v[44:45], v[30:31]
	v_mov_b32_e32 v48, v10
	v_mov_b32_e32 v49, v24
	v_mov_b32_e32 v29, v30
	v_pk_mul_f32 v[54:55], v[52:53], v[16:17]
	v_mov_b32_e32 v56, v12
	v_mov_b32_e32 v57, v25
	v_mov_b32_e32 v33, v34
	v_pk_fma_f32 v[30:31], v[44:45], v[30:31], v[44:45] neg_lo:[1,0,0] neg_hi:[1,0,0]
	v_mov_b32_e32 v37, v34
	v_pk_fma_f32 v[34:35], v[40:41], v[34:35], v[40:41] neg_lo:[1,0,0] neg_hi:[1,0,0]
	v_cndmask_b32_e64 v38, v14, v38, s[14:15]
	v_pk_fma_f32 v[14:15], v[52:53], v[16:17], v[52:53] neg_lo:[1,0,0] neg_hi:[1,0,0]
	v_cmp_gt_f32_e64 s[16:17], 0, v11
	v_pk_mul_f32 v[50:51], v[48:49], v[28:29]
	v_pk_mul_f32 v[58:59], v[56:57], v[32:33]
	v_pk_fma_f32 v[28:29], v[48:49], v[28:29], v[48:49] neg_lo:[1,0,0] neg_hi:[1,0,0]
	v_cmp_gt_f32_e32 vcc, 0, v24
	v_mov_b32_e32 v24, v13
	v_cmp_gt_f32_e64 s[18:19], 0, v10
	v_cndmask_b32_e64 v17, v31, v47, s[14:15]
	v_pk_fma_f32 v[26:27], v[56:57], v[32:33], v[56:57] neg_lo:[1,0,0] neg_hi:[1,0,0]
	v_cndmask_b32_e64 v31, v35, v43, s[14:15]
	v_cmp_gt_f32_e64 s[14:15], 0, v25
	v_cndmask_b32_e64 v32, v14, v54, s[16:17]
	v_mov_b32_e32 v14, v39
	v_pk_mul_f32 v[44:45], v[24:25], v[36:37]
	v_cndmask_b32_e32 v11, v29, v51, vcc
	v_cndmask_b32_e64 v10, v28, v50, s[18:19]
	v_cndmask_b32_e32 v16, v30, v46, vcc
	v_pk_fma_f32 v[28:29], v[24:25], v[36:37], v[24:25] neg_lo:[1,0,0] neg_hi:[1,0,0]
	v_cndmask_b32_e64 v30, v34, v42, s[14:15]
	v_cndmask_b32_e32 v33, v15, v55, vcc
	v_cmp_gt_f32_e32 vcc, 0, v12
	v_pk_add_f32 v[14:15], v[14:15], v[38:39] op_sel_hi:[0,1]
	v_pk_mul_f32 v[24:25], v[38:39], v[38:39]
	v_cmp_gt_f32_e64 s[18:19], 0, v13
	v_cndmask_b32_e64 v13, v27, v59, s[14:15]
	v_cndmask_b32_e32 v12, v26, v58, vcc
	v_mov_b32_e32 v15, v25
	v_pk_add_f32 v[24:25], v[16:17], v[30:31]
	v_pk_mul_f32 v[26:27], v[16:17], v[30:31]
	v_cndmask_b32_e64 v29, v29, v45, s[14:15]
	v_mov_b32_e32 v25, v27
	v_cndmask_b32_e64 v28, v28, v44, s[18:19]
	v_pk_add_f32 v[14:15], v[14:15], v[24:25]
	v_pk_add_f32 v[24:25], v[10:11], v[32:33]
	v_pk_mul_f32 v[26:27], v[10:11], v[32:33]
	v_pk_mul_f32 v[34:35], v[12:13], v[28:29]
	v_mov_b32_e32 v25, v27
	v_pk_add_f32 v[26:27], v[12:13], v[28:29]
	v_mov_b32_e32 v33, v28
	v_mov_b32_e32 v27, v35
	v_pk_add_f32 v[24:25], v[24:25], v[26:27]
	v_mov_b32_e32 v11, v12
	v_pk_add_f32 v[14:15], v[14:15], v[24:25]
	v_pk_mul_f32 v[24:25], v[32:33], v[32:33]
	v_mov_b32_e32 v26, v39
	v_pk_fma_f32 v[24:25], v[10:11], v[10:11], v[24:25]
	v_mov_b32_e32 v27, v38
	v_pk_add_f32 v[24:25], v[24:25], v[24:25] op_sel_hi:[0,1]
	v_mov_b32_e32 v139, v25
	v_pk_add_f32 v[14:15], v[14:15], v[138:139]
	v_mov_b32_e32 v24, v16
	v_mov_b32_e32 v25, v30
	v_mov_b32_e32 v11, v32
	v_mov_b32_e32 v13, v28
	s_branch .LBB0_647
